# P6: out-gain loads issued up front, S^T tile loads hoisted above masked-attn stage
# speedup vs baseline: 1.0157x; 1.0000x over previous
; #define LAS __attribute__((address_space(3)))
; __global__ void __launch_bounds__(NT, 2) hymba_fwd(Args args) {
;     ...
;               for (int q = 0; q < 4; ++q) { const int e = (q * NT + tid) * 8, rr = e >> 7, cc = e & 127; *(LAS u32x4*)(X1 + rr * XP + cc) = *(const u32x4*)(DST + (size_t)((c - 1) * 4 + h) * 16384 + e); } }
;             __syncthreads();
; #pragma unroll
;             for (int r = 0; r < 16; ++r) { acc[0][r] = 0.f; acc[1][r] = 0.f; }
;             mm128(lds + 0 * XB, lds + 3 * XB, acc, wave, lane);
;             mm128(lds + 2 * XB, lds + 1 * XB, acc, wave, lane);
.LBB0_1120:
	s_or_b64 exec, exec, s[0:1]
	s_movk_i32 s0, 0xa000
	v_add_co_u32_e32 v2, vcc, s0, v64
	s_movk_i32 s0, 0xc000
	s_nop 0
	v_addc_co_u32_e32 v3, vcc, -1, v65, vcc
	v_add_co_u32_e32 v6, vcc, s0, v64
	s_movk_i32 s0, 0xe000
	s_nop 0
	v_addc_co_u32_e32 v7, vcc, -1, v65, vcc
	v_add_co_u32_e32 v10, vcc, s0, v64
	s_nop 0
	v_addc_co_u32_e32 v11, vcc, -1, v65, vcc
	s_nop 0
	v_readlane_b32 s4, v237, 7
	v_readlane_b32 s5, v237, 8
	s_mov_b32 s0, 0xf800000
	v_readlane_b32 s18, v237, 21
	v_readlane_b32 s19, v237, 22
	s_lshl_b32 s2, s67, 1
	v_readlane_b32 s6, v237, 9
	v_readlane_b32 s7, v237, 10
	v_readlane_b32 s8, v237, 11
	v_readlane_b32 s9, v237, 12
	v_readlane_b32 s10, v237, 13
	v_readlane_b32 s11, v237, 14
	v_readlane_b32 s12, v237, 15
	v_readlane_b32 s13, v237, 16
	v_readlane_b32 s14, v237, 17
	v_readlane_b32 s15, v237, 18
	v_readlane_b32 s16, v237, 19
	v_readlane_b32 s17, v237, 20
	ds_write_b16 v155, v0 offset:7408
	s_waitcnt vmcnt(3)
	ds_write_b128 v141, v[160:163] offset:34816
	s_waitcnt vmcnt(2)
	ds_write_b128 v142, v[164:167] offset:34816
	s_waitcnt vmcnt(1)
	ds_write_b128 v143, v[168:171] offset:34816
	s_waitcnt vmcnt(0)
	ds_write_b128 v144, v[172:175] offset:34816
	s_waitcnt lgkmcnt(0)
	s_barrier
	ds_read_b128 v[16:19], v153
	ds_read_b128 v[0:3], v145
	ds_read_b128 v[50:53], v153 offset:32
	ds_read_b128 v[66:69], v145 offset:32
	s_waitcnt lgkmcnt(2)
	v_mfma_f32_32x32x16_bf16 v[0:15], v[16:19], v[0:3], 0
	ds_read_b128 v[20:23], v145 offset:8704
	ds_read_b128 v[70:73], v145 offset:8736
	s_waitcnt lgkmcnt(1)
	v_mfma_f32_32x32x16_bf16 v[16:31], v[16:19], v[20:23], 0
	v_mfma_f32_32x32x16_bf16 v[0:15], v[50:53], v[66:69], v[0:15]
	s_waitcnt lgkmcnt(0)
	v_mfma_f32_32x32x16_bf16 v[16:31], v[50:53], v[70:73], v[16:31]
	ds_read_b128 v[50:53], v153 offset:64
	ds_read_b128 v[66:69], v145 offset:64
	ds_read_b128 v[70:73], v153 offset:96
	ds_read_b128 v[74:77], v145 offset:96
	s_waitcnt lgkmcnt(2)
	v_mfma_f32_32x32x16_bf16 v[0:15], v[50:53], v[66:69], v[0:15]
	ds_read_b128 v[66:69], v145 offset:8768
	ds_read_b128 v[78:81], v145 offset:8800
	s_waitcnt lgkmcnt(1)
	v_mfma_f32_32x32x16_bf16 v[16:31], v[50:53], v[66:69], v[16:31]
	v_mfma_f32_32x32x16_bf16 v[0:15], v[70:73], v[74:77], v[0:15]
	s_waitcnt lgkmcnt(0)
	v_mfma_f32_32x32x16_bf16 v[16:31], v[70:73], v[78:81], v[16:31]
	ds_read_b128 v[50:53], v153 offset:128
	ds_read_b128 v[66:69], v145 offset:128
	ds_read_b128 v[70:73], v153 offset:160
	ds_read_b128 v[74:77], v145 offset:160
	s_waitcnt lgkmcnt(2)
	v_mfma_f32_32x32x16_bf16 v[0:15], v[50:53], v[66:69], v[0:15]
	ds_read_b128 v[66:69], v145 offset:8832
	ds_read_b128 v[78:81], v145 offset:8864
	s_waitcnt lgkmcnt(1)
	v_mfma_f32_32x32x16_bf16 v[16:31], v[50:53], v[66:69], v[16:31]
	v_mfma_f32_32x32x16_bf16 v[0:15], v[70:73], v[74:77], v[0:15]
	s_waitcnt lgkmcnt(0)
	v_mfma_f32_32x32x16_bf16 v[16:31], v[70:73], v[78:81], v[16:31]
	ds_read_b128 v[50:53], v153 offset:192
	ds_read_b128 v[66:69], v145 offset:192
	ds_read_b128 v[70:73], v153 offset:224
	ds_read_b128 v[74:77], v145 offset:224
	s_waitcnt lgkmcnt(2)
	v_mfma_f32_32x32x16_bf16 v[0:15], v[50:53], v[66:69], v[0:15]
	ds_read_b128 v[66:69], v145 offset:8896
	ds_read_b128 v[78:81], v145 offset:8928
	s_waitcnt lgkmcnt(1)
	v_mfma_f32_32x32x16_bf16 v[16:31], v[50:53], v[66:69], v[16:31]
	v_mfma_f32_32x32x16_bf16 v[0:15], v[70:73], v[74:77], v[0:15]
	s_waitcnt lgkmcnt(0)
	v_mfma_f32_32x32x16_bf16 v[16:31], v[70:73], v[78:81], v[16:31]
	ds_read_b128 v[50:53], v146
	ds_read_b128 v[66:69], v154 offset:34816
	ds_read_b128 v[70:73], v146 offset:32
	ds_read_b128 v[74:77], v154 offset:34848
	s_waitcnt lgkmcnt(2)
	v_mfma_f32_32x32x16_bf16 v[0:15], v[50:53], v[66:69], v[0:15]
	ds_read_b128 v[66:69], v154 offset:43520
	ds_read_b128 v[78:81], v154 offset:43552
	s_waitcnt lgkmcnt(1)
	v_mfma_f32_32x32x16_bf16 v[16:31], v[50:53], v[66:69], v[16:31]
	v_mfma_f32_32x32x16_bf16 v[0:15], v[70:73], v[74:77], v[0:15]
	s_waitcnt lgkmcnt(0)
	v_mfma_f32_32x32x16_bf16 v[16:31], v[70:73], v[78:81], v[16:31]
	ds_read_b128 v[50:53], v146 offset:64
	ds_read_b128 v[66:69], v154 offset:34880
	ds_read_b128 v[70:73], v146 offset:96
	ds_read_b128 v[74:77], v154 offset:34912
	s_waitcnt lgkmcnt(2)
	v_mfma_f32_32x32x16_bf16 v[0:15], v[50:53], v[66:69], v[0:15]
	ds_read_b128 v[66:69], v154 offset:43584
	ds_read_b128 v[78:81], v154 offset:43616
	s_waitcnt lgkmcnt(1)
	v_mfma_f32_32x32x16_bf16 v[16:31], v[50:53], v[66:69], v[16:31]
	v_mfma_f32_32x32x16_bf16 v[0:15], v[70:73], v[74:77], v[0:15]
	s_waitcnt lgkmcnt(0)
	v_mfma_f32_32x32x16_bf16 v[16:31], v[70:73], v[78:81], v[16:31]
	ds_read_b128 v[50:53], v146 offset:128
	ds_read_b128 v[66:69], v154 offset:34944
	ds_read_b128 v[70:73], v146 offset:160
	ds_read_b128 v[74:77], v154 offset:34976
	s_waitcnt lgkmcnt(2)
	v_mfma_f32_32x32x16_bf16 v[0:15], v[50:53], v[66:69], v[0:15]
	ds_read_b128 v[66:69], v154 offset:43648
	ds_read_b128 v[78:81], v154 offset:43680
	s_waitcnt lgkmcnt(1)
	v_mfma_f32_32x32x16_bf16 v[16:31], v[50:53], v[66:69], v[16:31]
	v_mfma_f32_32x32x16_bf16 v[0:15], v[70:73], v[74:77], v[0:15]
	s_waitcnt lgkmcnt(0)
	v_mfma_f32_32x32x16_bf16 v[16:31], v[70:73], v[78:81], v[16:31]
	ds_read_b128 v[50:53], v146 offset:192
	ds_read_b128 v[66:69], v154 offset:35008
	ds_read_b128 v[70:73], v146 offset:224
	ds_read_b128 v[74:77], v154 offset:35040
	s_waitcnt lgkmcnt(2)
	v_mfma_f32_32x32x16_bf16 v[0:15], v[50:53], v[66:69], v[0:15]
	ds_read_b128 v[66:69], v154 offset:43712
	ds_read_b128 v[78:81], v154 offset:43744
	s_waitcnt lgkmcnt(0)
	s_barrier
; #define LAS __attribute__((address_space(3)))
; __device__ __forceinline__ unsigned pk2(float lo, float hi) { return f2bf(lo) | (f2bf(hi) << 16); }
; __device__ __forceinline__ int crow(int r, int hi) { return (r & 3) + 8 * (r >> 2) + 4 * hi; }
; __global__ void __launch_bounds__(NT, 2) hymba_fwd(Args args) {
;     ...
;             __syncthreads();
;             LAS float* OB = (LAS float*)lds;
;             { const int l32 = lane & 31, hh = lane >> 5;
; #pragma unroll
;               for (int nt = 0; nt < 2; ++nt)
; #pragma unroll
;                 for (int r = 0; r < 16; ++r) OB[((wave & 3) * 32 + crow(r, hh)) * 132 + (wave >> 2) * 64 + 32 * nt + l32] = acc[nt][r]; }
;             __syncthreads();
;             { const int row = tid >> 2, part = tid & 3; const LAS float* orow = OB + row * 132 + part * 32; float ov[32]; float sq = 0.f;
; #pragma unroll
;               for (int e = 0; e < 32; ++e) { ov[e] = orow[e]; sq += ov[e] * ov[e]; }
;               sq += __shfl_xor(sq, 1); sq += __shfl_xor(sq, 2);
;               const float rn = 1.0f / sqrtf(sq * (1.0f / 128.0f) + 1e-6f);
;               const size_t g = (size_t)(rbase + row) * 512 + h * 128 + part * 32;
; #pragma unroll
;               for (int q = 0; q < 4; ++q) { const u32x4 gt = ghv[q]; u32x4 o;
; #pragma unroll
;                   for (int e = 0; e < 4; ++e) { const int cidx = 8 * q + 2 * e; const float g0 = __builtin_bit_cast(float, gt[e] << 16), g1 = __builtin_bit_cast(float, gt[e] & 0xffff0000u);
;                       o[e] = pk2(ov[cidx] * rn * og[h * 128 + part * 32 + cidx] * g0, ov[cidx + 1] * rn * og[h * 128 + part * 32 + cidx + 1] * g1); }
	v_mfma_f32_32x32x16_bf16 v[16:31], v[50:53], v[66:69], v[16:31]
	v_lshlrev_b32_e32 v67, 16, v45
	v_lshlrev_b32_e32 v66, 16, v44
	v_and_b32_e32 v69, 0xffff0000, v45
	v_and_b32_e32 v68, 0xffff0000, v44
	v_mfma_f32_32x32x16_bf16 v[0:15], v[70:73], v[74:77], v[0:15]
	v_mfma_f32_32x32x16_bf16 v[16:31], v[70:73], v[78:81], v[16:31]
	s_nop 11
	ds_write2_b32 v147, v0, v16 offset1:32
	ds_write2_b32 v147, v1, v17 offset0:132 offset1:164
	v_add_u32_e32 v0, 0x400, v147
	ds_write2_b32 v0, v2, v18 offset0:8 offset1:40
	ds_write2_b32 v0, v3, v19 offset0:140 offset1:172
	v_add_u32_e32 v0, 0x1000, v147
	ds_write2_b32 v0, v4, v20 offset0:32 offset1:64
	ds_write2_b32 v0, v5, v21 offset0:164 offset1:196
	v_add_u32_e32 v0, 0x1400, v147
	ds_write2_b32 v0, v6, v22 offset0:40 offset1:72
	ds_write2_b32 v0, v7, v23 offset0:172 offset1:204
	v_add_u32_e32 v0, 0x2000, v147
	ds_write2_b32 v0, v8, v24 offset0:64 offset1:96
	ds_write2_b32 v0, v9, v25 offset0:196 offset1:228
	v_add_u32_e32 v0, 0x2400, v147
	ds_write2_b32 v0, v10, v26 offset0:72 offset1:104
	ds_write2_b32 v0, v11, v27 offset0:204 offset1:236
	v_add_u32_e32 v0, 0x3000, v147
	ds_write2_b32 v0, v12, v28 offset0:96 offset1:128
	v_add_u32_e32 v0, 0x3200, v147
	ds_write2_b32 v0, v13, v29 offset0:100 offset1:132
	v_add_u32_e32 v0, 0x3400, v147
	v_or_b32_e32 v8, s67, v60
	ds_write2_b32 v0, v14, v30 offset0:104 offset1:136
	v_add_u32_e32 v0, 0x3600, v147
	v_lshlrev_b32_e32 v72, 2, v8
	ds_write2_b32 v0, v15, v31 offset0:108 offset1:140
	s_waitcnt lgkmcnt(0)
	s_barrier
	ds_read_b128 v[0:3], v103 offset:96
	ds_read_b128 v[4:7], v103 offset:112
	v_lshlrev_b64 v[80:81], 11, v[48:49]
	ds_read_b128 v[28:31], v103
	ds_read_b128 v[24:27], v103 offset:16
	ds_read_b128 v[12:15], v103 offset:32
	ds_read_b128 v[8:11], v103 offset:48
	global_load_dwordx4 v[48:51], v72, s[4:5] offset:16
	global_load_dwordx4 v[52:55], v72, s[4:5]
	global_load_dwordx4 v[180:183], v72, s[4:5] offset:32
	global_load_dwordx4 v[184:187], v72, s[4:5] offset:48
	global_load_dwordx4 v[188:191], v72, s[4:5] offset:64
	global_load_dwordx4 v[192:195], v72, s[4:5] offset:80
	global_load_dwordx4 v[196:199], v72, s[4:5] offset:96
	global_load_dwordx4 v[200:203], v72, s[4:5] offset:112
	ds_read_b128 v[16:19], v103 offset:64
	ds_read_b128 v[20:23], v103 offset:80
	s_waitcnt lgkmcnt(5)
	v_pk_mul_f32 v[84:85], v[28:29], v[28:29]
	v_pk_mul_f32 v[82:83], v[30:31], v[30:31]
	v_add_f32_e32 v70, v84, v85
	v_add_f32_e32 v70, v70, v82
	s_waitcnt lgkmcnt(4)
	v_pk_mul_f32 v[86:87], v[24:25], v[24:25]
	v_add_f32_e32 v70, v70, v83
	v_add_f32_e32 v70, v70, v86
	v_pk_mul_f32 v[44:45], v[26:27], v[26:27]
	v_add_f32_e32 v70, v70, v87
	v_add_f32_e32 v44, v70, v44
	s_waitcnt lgkmcnt(3)
	v_pk_mul_f32 v[90:91], v[12:13], v[12:13]
	v_add_f32_e32 v44, v44, v45
	v_add_f32_e32 v44, v44, v90
	v_pk_mul_f32 v[88:89], v[14:15], v[14:15]
	v_add_f32_e32 v44, v44, v91
	v_add_f32_e32 v44, v44, v88
	s_waitcnt lgkmcnt(2)
	v_pk_mul_f32 v[94:95], v[8:9], v[8:9]
	v_add_f32_e32 v44, v44, v89
	v_add_f32_e32 v44, v44, v94
	v_pk_mul_f32 v[92:93], v[10:11], v[10:11]
	v_add_f32_e32 v44, v44, v95
	v_add_f32_e32 v44, v44, v92
	s_waitcnt lgkmcnt(1)
	v_pk_mul_f32 v[98:99], v[16:17], v[16:17]
	v_add_f32_e32 v44, v44, v93
	v_add_f32_e32 v44, v44, v98
	v_pk_mul_f32 v[96:97], v[18:19], v[18:19]
	v_add_f32_e32 v44, v44, v99
	v_add_f32_e32 v44, v44, v96
	s_waitcnt lgkmcnt(0)
	v_pk_mul_f32 v[158:159], v[20:21], v[20:21]
	v_add_f32_e32 v44, v44, v97
	v_add_f32_e32 v44, v44, v158
	v_pk_mul_f32 v[156:157], v[22:23], v[22:23]
	v_add_f32_e32 v44, v44, v159
	v_add_f32_e32 v44, v44, v156
	v_add_f32_e32 v44, v44, v157
	v_fmac_f32_e32 v44, v0, v0
	v_pk_mul_f32 v[74:75], v[2:3], v[2:3]
	v_fmac_f32_e32 v44, v1, v1
	v_add_f32_e32 v44, v44, v74
	v_pk_mul_f32 v[76:77], v[4:5], v[4:5]
	v_add_f32_e32 v44, v44, v75
	v_add_f32_e32 v44, v44, v76
	v_pk_mul_f32 v[78:79], v[6:7], v[6:7]
	v_add_f32_e32 v44, v44, v77
	v_add_f32_e32 v44, v44, v78
	v_add_f32_e32 v73, v44, v79
	ds_bpermute_b32 v74, v104, v73
	v_mov_b32_e32 v75, v30
	v_lshlrev_b32_e32 v71, 16, v47
	v_lshlrev_b32_e32 v70, 16, v46
	v_and_b32_e32 v47, 0xffff0000, v47
	s_waitcnt lgkmcnt(0)
	v_add_f32_e32 v73, v73, v74
	ds_bpermute_b32 v76, v105, v73
	v_mov_b32_e32 v74, v28
	v_and_b32_e32 v46, 0xffff0000, v46
	v_lshl_add_u64 v[44:45], s[18:19], 0, v[80:81]
	v_lshl_add_u64 v[44:45], v[44:45], 0, s[2:3]
	s_waitcnt lgkmcnt(0)
	v_add_f32_e32 v28, v73, v76
	v_fmamk_f32 v28, v28, 0x3c000000, v148
	v_mul_f32_e32 v30, 0x4f800000, v28
	v_cmp_gt_f32_e32 vcc, s0, v28
	v_lshl_add_u64 v[44:45], v[44:45], 0, v[58:59]
	v_readlane_b32 s2, v237, 50
	v_cndmask_b32_e32 v73, v28, v30, vcc
	v_sqrt_f32_e32 v76, v73
	v_mov_b32_e32 v28, v24
	v_mov_b32_e32 v30, v29
	v_mov_b32_e32 v29, v26
	v_add_u32_e32 v24, -1, v76
	v_add_u32_e32 v26, 1, v76
	v_fma_f32 v77, -v24, v76, v73
	v_fma_f32 v78, -v26, v76, v73
	v_cmp_ge_f32_e64 s[0:1], 0, v77
	s_nop 1
	v_cndmask_b32_e64 v24, v76, v24, s[0:1]
	v_cmp_lt_f32_e64 s[0:1], 0, v78
	s_nop 1
	v_cndmask_b32_e64 v24, v24, v26, s[0:1]
	v_mul_f32_e32 v26, 0x37800000, v24
	v_cndmask_b32_e32 v24, v24, v26, vcc
	v_cmp_class_f32_e32 vcc, v73, v149
	v_mov_b32_e32 v26, v25
	s_nop 0
	v_cndmask_b32_e32 v24, v24, v73, vcc
	v_div_scale_f32 v73, s[0:1], v24, v24, 1.0
	v_rcp_f32_e32 v76, v73
	v_div_scale_f32 v25, vcc, 1.0, v24, 1.0
	v_readlane_b32 s0, v237, 0
	v_fma_f32 v77, -v73, v76, 1.0
	v_fmac_f32_e32 v76, v77, v76
	v_mul_f32_e32 v77, v25, v76
	v_fma_f32 v78, -v73, v77, v25
	v_fmac_f32_e32 v77, v78, v76
	v_fma_f32 v25, -v73, v77, v25
	v_div_fmas_f32 v25, v25, v76, v77
	v_div_fixup_f32 v24, v25, v24, 1.0
	v_pk_mul_f32 v[74:75], v[24:25], v[74:75] op_sel_hi:[0,1]
	v_pk_mul_f32 v[28:29], v[24:25], v[28:29] op_sel_hi:[0,1]
	v_pk_mul_f32 v[26:27], v[24:25], v[26:27] op_sel_hi:[0,1]
	s_waitcnt vmcnt(0)
; __device__ __forceinline__ unsigned pk2(float lo, float hi) { return f2bf(lo) | (f2bf(hi) << 16); }
; __global__ void __launch_bounds__(NT, 2) hymba_fwd(Args args) {
;     ...
;               for (int q = 0; q < 4; ++q) { const u32x4 gt = ghv[q]; u32x4 o;
; #pragma unroll
;                   for (int e = 0; e < 4; ++e) { const int cidx = 8 * q + 2 * e; const float g0 = __builtin_bit_cast(float, gt[e] << 16), g1 = __builtin_bit_cast(float, gt[e] & 0xffff0000u);
;                       o[e] = pk2(ov[cidx] * rn * og[h * 128 + part * 32 + cidx] * g0, ov[cidx + 1] * rn * og[h * 128 + part * 32 + cidx + 1] * g1); }
;                   *(u32x4*)(OMIX + (size_t)(rbase + row) * 1024 + h * 128 + part * 32 + 8 * q) = o; } }
	v_mov_b32_e32 v76, v52
	v_mov_b32_e32 v77, v54
	v_mov_b32_e32 v54, v53
	v_mov_b32_e32 v52, v48
	v_mov_b32_e32 v53, v50
	v_mov_b32_e32 v50, v49
	v_pk_mul_f32 v[30:31], v[24:25], v[30:31] op_sel_hi:[0,1]
	v_pk_mul_f32 v[48:49], v[74:75], v[76:77]
	v_pk_mul_f32 v[28:29], v[28:29], v[52:53]
	v_pk_mul_f32 v[26:27], v[26:27], v[50:51]
	v_pk_mul_f32 v[30:31], v[30:31], v[54:55]
	v_pk_mul_f32 v[48:49], v[48:49], v[66:67]
	v_pk_mul_f32 v[28:29], v[28:29], v[70:71]
	v_pk_mul_f32 v[26:27], v[26:27], v[46:47]
	v_pk_mul_f32 v[30:31], v[30:31], v[68:69]
	v_bfe_u32 v25, v27, 16, 1
	v_bfe_u32 v46, v26, 16, 1
	v_bfe_u32 v51, v48, 16, 1
	v_bfe_u32 v52, v49, 16, 1
	v_bfe_u32 v53, v28, 16, 1
	v_bfe_u32 v54, v29, 16, 1
	v_bfe_u32 v47, v31, 16, 1
	v_bfe_u32 v50, v30, 16, 1
	v_add3_u32 v26, v26, v46, s64
	v_add3_u32 v25, v27, v25, s64
	v_add3_u32 v27, v29, v54, s64
	v_add3_u32 v28, v28, v53, s64
	v_add3_u32 v29, v49, v52, s64
	v_add3_u32 v46, v48, v51, s64
	v_add3_u32 v30, v30, v50, s64
	v_add3_u32 v31, v31, v47, s64
	v_lshrrev_b32_e32 v46, 16, v46
	v_lshrrev_b32_e32 v47, 16, v29
	v_lshrrev_b32_e32 v28, 16, v28
	v_lshrrev_b32_e32 v27, 16, v27
	v_and_or_b32 v29, v25, s65, v27
	v_and_or_b32 v28, v26, s65, v28
	v_and_or_b32 v27, v31, s65, v47
	v_and_or_b32 v26, v30, s65, v46
	global_store_dwordx4 v[44:45], v[26:29], off
	s_nop 1
	v_mov_b32_e32 v26, v180
	v_mov_b32_e32 v27, v181
	v_mov_b32_e32 v28, v182
	v_mov_b32_e32 v29, v183
	s_nop 0
	v_mov_b32_e32 v46, v184
	v_mov_b32_e32 v47, v185
	v_mov_b32_e32 v48, v186
	v_mov_b32_e32 v49, v187
	v_mov_b32_e32 v52, v12
	v_mov_b32_e32 v53, v14
	v_mov_b32_e32 v14, v13
	v_mov_b32_e32 v12, v8
	v_mov_b32_e32 v13, v10
	v_mov_b32_e32 v10, v9
	v_pk_mul_f32 v[8:9], v[24:25], v[52:53] op_sel_hi:[0,1]
	v_pk_mul_f32 v[12:13], v[24:25], v[12:13] op_sel_hi:[0,1]
	v_lshlrev_b32_e32 v31, 16, v41
	v_lshlrev_b32_e32 v30, 16, v40
	v_lshlrev_b32_e32 v51, 16, v43
	v_lshlrev_b32_e32 v50, 16, v42
	v_pk_mul_f32 v[14:15], v[24:25], v[14:15] op_sel_hi:[0,1]
	v_pk_mul_f32 v[10:11], v[24:25], v[10:11] op_sel_hi:[0,1]
	v_and_b32_e32 v41, 0xffff0000, v41
	v_and_b32_e32 v40, 0xffff0000, v40
	v_and_b32_e32 v43, 0xffff0000, v43
	v_and_b32_e32 v42, 0xffff0000, v42
	s_add_i32 s66, s66, s0
	v_readlane_b32 s0, v236, 39
	v_readlane_b32 s1, v237, 1
	s_add_i32 s2, s2, s0
	v_readlane_b32 s0, v236, 42
	v_mov_b32_e32 v52, v26
	v_mov_b32_e32 v53, v28
	v_mov_b32_e32 v28, v27
	v_mov_b32_e32 v26, v46
	v_mov_b32_e32 v27, v48
	v_mov_b32_e32 v48, v47
	v_pk_mul_f32 v[8:9], v[8:9], v[52:53]
	v_pk_mul_f32 v[12:13], v[12:13], v[26:27]
	v_pk_mul_f32 v[14:15], v[14:15], v[28:29]
	v_pk_mul_f32 v[10:11], v[10:11], v[48:49]
	v_pk_mul_f32 v[8:9], v[8:9], v[30:31]
	v_pk_mul_f32 v[12:13], v[12:13], v[50:51]
	v_pk_mul_f32 v[14:15], v[14:15], v[40:41]
	v_pk_mul_f32 v[10:11], v[10:11], v[42:43]
	v_bfe_u32 v29, v8, 16, 1
	v_bfe_u32 v30, v9, 16, 1
	v_bfe_u32 v31, v12, 16, 1
	v_bfe_u32 v40, v13, 16, 1
	v_bfe_u32 v25, v11, 16, 1
	v_bfe_u32 v26, v10, 16, 1
	v_bfe_u32 v27, v15, 16, 1
	v_bfe_u32 v28, v14, 16, 1
	v_add3_u32 v13, v13, v40, s64
	v_add3_u32 v12, v12, v31, s64
	v_add3_u32 v9, v9, v30, s64
	v_add3_u32 v8, v8, v29, s64
	v_add3_u32 v14, v14, v28, s64
	v_add3_u32 v15, v15, v27, s64
	v_add3_u32 v10, v10, v26, s64
	v_add3_u32 v11, v11, v25, s64
	v_lshrrev_b32_e32 v8, 16, v8
	v_lshrrev_b32_e32 v9, 16, v9
	v_lshrrev_b32_e32 v12, 16, v12
	v_lshrrev_b32_e32 v13, 16, v13
	v_and_or_b32 v11, v11, s65, v13
	v_and_or_b32 v10, v10, s65, v12
	v_and_or_b32 v9, v15, s65, v9
	v_and_or_b32 v8, v14, s65, v8
	global_store_dwordx4 v[44:45], v[8:11], off offset:16
	s_nop 1
	v_mov_b32_e32 v8, v188
	v_mov_b32_e32 v9, v189
	v_mov_b32_e32 v10, v190
	v_mov_b32_e32 v11, v191
	s_nop 0
	v_mov_b32_e32 v12, v192
	v_mov_b32_e32 v13, v193
	v_mov_b32_e32 v14, v194
	v_mov_b32_e32 v15, v195
	v_lshlrev_b32_e32 v27, 16, v37
	v_lshlrev_b32_e32 v26, 16, v36
	v_and_b32_e32 v29, 0xffff0000, v37
	v_and_b32_e32 v28, 0xffff0000, v36
	v_lshlrev_b32_e32 v31, 16, v39
; __device__ __forceinline__ unsigned pk2(float lo, float hi) { return f2bf(lo) | (f2bf(hi) << 16); }
; __global__ void __launch_bounds__(NT, 2) hymba_fwd(Args args) {
;     ...
;               for (int q = 0; q < 4; ++q) { const u32x4 gt = ghv[q]; u32x4 o;
; #pragma unroll
;                   for (int e = 0; e < 4; ++e) { const int cidx = 8 * q + 2 * e; const float g0 = __builtin_bit_cast(float, gt[e] << 16), g1 = __builtin_bit_cast(float, gt[e] & 0xffff0000u);
;                       o[e] = pk2(ov[cidx] * rn * og[h * 128 + part * 32 + cidx] * g0, ov[cidx + 1] * rn * og[h * 128 + part * 32 + cidx + 1] * g1); }
;                   *(u32x4*)(OMIX + (size_t)(rbase + row) * 1024 + h * 128 + part * 32 + 8 * q) = o; } }
	v_lshlrev_b32_e32 v30, 16, v38
	v_and_b32_e32 v37, 0xffff0000, v39
	v_and_b32_e32 v36, 0xffff0000, v38
	v_mov_b32_e32 v38, v16
	v_mov_b32_e32 v39, v18
	v_mov_b32_e32 v18, v17
	v_mov_b32_e32 v16, v20
	v_mov_b32_e32 v17, v22
	v_mov_b32_e32 v22, v21
	v_pk_mul_f32 v[20:21], v[24:25], v[38:39] op_sel_hi:[0,1]
	v_pk_mul_f32 v[16:17], v[24:25], v[16:17] op_sel_hi:[0,1]
	v_pk_mul_f32 v[18:19], v[24:25], v[18:19] op_sel_hi:[0,1]
	v_pk_mul_f32 v[22:23], v[24:25], v[22:23] op_sel_hi:[0,1]
	v_mov_b32_e32 v38, v8
	v_mov_b32_e32 v39, v10
	v_mov_b32_e32 v10, v9
	v_mov_b32_e32 v8, v12
	v_mov_b32_e32 v9, v14
	v_mov_b32_e32 v14, v13
	v_pk_mul_f32 v[12:13], v[20:21], v[38:39]
	v_pk_mul_f32 v[8:9], v[16:17], v[8:9]
	v_pk_mul_f32 v[10:11], v[18:19], v[10:11]
	v_pk_mul_f32 v[14:15], v[22:23], v[14:15]
	v_pk_mul_f32 v[12:13], v[12:13], v[26:27]
	v_pk_mul_f32 v[8:9], v[8:9], v[30:31]
	v_pk_mul_f32 v[10:11], v[10:11], v[28:29]
	v_pk_mul_f32 v[14:15], v[14:15], v[36:37]
	v_bfe_u32 v20, v12, 16, 1
	v_bfe_u32 v21, v13, 16, 1
	v_bfe_u32 v22, v8, 16, 1
	v_bfe_u32 v23, v9, 16, 1
	v_bfe_u32 v16, v15, 16, 1
	v_bfe_u32 v17, v14, 16, 1
	v_bfe_u32 v18, v11, 16, 1
	v_bfe_u32 v19, v10, 16, 1
	v_add3_u32 v9, v9, v23, s64
	v_add3_u32 v8, v8, v22, s64
	v_add3_u32 v13, v13, v21, s64
	v_add3_u32 v12, v12, v20, s64
	v_add3_u32 v19, v10, v19, s64
	v_add3_u32 v18, v11, v18, s64
	v_add3_u32 v10, v14, v17, s64
	v_add3_u32 v11, v15, v16, s64
	v_lshrrev_b32_e32 v12, 16, v12
	v_lshrrev_b32_e32 v13, 16, v13
	v_lshrrev_b32_e32 v8, 16, v8
	v_lshrrev_b32_e32 v9, 16, v9
	v_and_or_b32 v11, v11, s65, v9
	v_and_or_b32 v10, v10, s65, v8
	v_and_or_b32 v9, v18, s65, v13
	v_and_or_b32 v8, v19, s65, v12
	global_store_dwordx4 v[44:45], v[8:11], off offset:32
	s_nop 1
	v_mov_b32_e32 v8, v196
	v_mov_b32_e32 v9, v197
	v_mov_b32_e32 v10, v198
	v_mov_b32_e32 v11, v199
	s_nop 0
	v_mov_b32_e32 v12, v200
	v_mov_b32_e32 v13, v201
	v_mov_b32_e32 v14, v202
	v_mov_b32_e32 v15, v203
	v_mov_b32_e32 v26, v0
	v_mov_b32_e32 v27, v2
	v_mov_b32_e32 v2, v1
	v_mov_b32_e32 v0, v4
	v_mov_b32_e32 v1, v6
	v_mov_b32_e32 v6, v5
	v_pk_mul_f32 v[4:5], v[24:25], v[26:27] op_sel_hi:[0,1]
	v_pk_mul_f32 v[2:3], v[24:25], v[2:3] op_sel_hi:[0,1]
	v_pk_mul_f32 v[0:1], v[24:25], v[0:1] op_sel_hi:[0,1]
	v_pk_mul_f32 v[6:7], v[24:25], v[6:7] op_sel_hi:[0,1]
	v_lshlrev_b32_e32 v17, 16, v33
	v_lshlrev_b32_e32 v16, 16, v32
	v_lshlrev_b32_e32 v21, 16, v35
	v_lshlrev_b32_e32 v20, 16, v34
	v_and_b32_e32 v19, 0xffff0000, v33
	v_and_b32_e32 v18, 0xffff0000, v32
	v_and_b32_e32 v23, 0xffff0000, v35
	v_and_b32_e32 v22, 0xffff0000, v34
	v_readlane_b32 s5, v237, 31
	s_add_i32 s5, s5, s0
	v_readlane_b32 s0, v236, 40
	v_readlane_b32 s1, v236, 41
	s_cmpk_lt_i32 s66, 0x200
	v_mov_b32_e32 v24, v8
	v_mov_b32_e32 v25, v10
	v_mov_b32_e32 v10, v9
	v_mov_b32_e32 v8, v12
	v_mov_b32_e32 v9, v14
	v_mov_b32_e32 v14, v13
	v_pk_mul_f32 v[4:5], v[4:5], v[24:25]
	v_pk_mul_f32 v[0:1], v[0:1], v[8:9]
	v_pk_mul_f32 v[2:3], v[2:3], v[10:11]
	v_pk_mul_f32 v[6:7], v[6:7], v[14:15]
	v_pk_mul_f32 v[4:5], v[4:5], v[16:17]
	v_pk_mul_f32 v[0:1], v[0:1], v[20:21]
	v_pk_mul_f32 v[2:3], v[2:3], v[18:19]
	v_pk_mul_f32 v[6:7], v[6:7], v[22:23]
	v_bfe_u32 v12, v4, 16, 1
	v_bfe_u32 v13, v5, 16, 1
	v_bfe_u32 v14, v0, 16, 1
	v_bfe_u32 v15, v1, 16, 1
	v_bfe_u32 v8, v7, 16, 1
	v_bfe_u32 v9, v6, 16, 1
	v_bfe_u32 v10, v3, 16, 1
	v_bfe_u32 v11, v2, 16, 1
	v_add3_u32 v1, v1, v15, s64
	v_add3_u32 v0, v0, v14, s64
	v_add3_u32 v5, v5, v13, s64
	v_add3_u32 v4, v4, v12, s64
	v_add3_u32 v11, v2, v11, s64
	v_add3_u32 v10, v3, v10, s64
	v_add3_u32 v2, v6, v9, s64
	v_add3_u32 v3, v7, v8, s64
	v_lshrrev_b32_e32 v4, 16, v4
	v_lshrrev_b32_e32 v5, 16, v5
	v_lshrrev_b32_e32 v0, 16, v0
	v_lshrrev_b32_e32 v1, 16, v1
	v_and_or_b32 v3, v3, s65, v1
	v_and_or_b32 v2, v2, s65, v0
	v_and_or_b32 v1, v10, s65, v5
	v_and_or_b32 v0, v11, s65, v4
	v_lshl_add_u64 v[64:65], v[64:65], 0, s[0:1]
	global_store_dwordx4 v[44:45], v[0:3], off offset:48
	s_barrier
	s_cbranch_scc0 .LBB0_1193

; __device__ __forceinline__ void hg_gates(const float* ZF, const float* LB, int c, int h, int d, int seg, float (&lf)[32], float (&kk)[32], float& pre, float& tot, float& ref, LAS float* SEG) {
;     ...
;     for (int i = 0; i < 32; ++i) { const bool valid = 128 * c + 32 * seg + i >= 112; const float z = fminf(fmaxf(zr[i], -30.f), 30.f);
;         const float en = __expf(-z), sg = __builtin_amdgcn_rcpf(1.0f + en); lf[i] = valid ? __logf(lb + (1.0f - lb) * sg) : 0.f; kk[i] = valid ? (1.0f - lb) * en * sg : 0.f;
; __global__ void __launch_bounds__(NT, 2) hymba_fwd(Args args) {
;     ...
;             for (int i = 0; i < 32; ++i) { const size_t g = (size_t)(rbase + 32 * seg + i) * 512 + h * 128 + d; qr[i] = __builtin_nontemporal_load(QH + g); vr[i] = __builtin_nontemporal_load(VH + g); }
.LBB0_1129:
	s_or_b64 exec, exec, s[50:51]
	v_mul_f32_e32 v1, v15, v5
	v_mul_f32_e32 v1, v1, v7
	v_cndmask_b32_e64 v95, 0, v1, s[4:5]
	v_mul_f32_e32 v1, v15, v3
	v_mul_f32_e32 v1, v1, v9
	v_cndmask_b32_e64 v93, 0, v1, s[70:71]
	v_mul_f32_e32 v1, v15, v11
	v_mul_f32_e32 v1, v1, v13
	v_cndmask_b32_e64 v91, 0, v1, s[72:73]
	v_mul_f32_e32 v1, v15, v19
	v_mul_f32_e32 v1, v1, v21
	v_cndmask_b32_e64 v89, 0, v1, s[74:75]
	v_mul_f32_e32 v1, v15, v23
	v_mul_f32_e32 v1, v1, v25
	v_cndmask_b32_e64 v87, 0, v1, s[76:77]
	v_mul_f32_e32 v1, v15, v31
	v_mul_f32_e32 v1, v1, v51
	v_cndmask_b32_e64 v3, 0, v1, s[78:79]
	v_mul_f32_e32 v1, v15, v55
	v_mul_f32_e32 v1, v1, v67
	v_cndmask_b32_e64 v85, 0, v1, s[80:81]
	v_mul_f32_e32 v1, v15, v71
	v_mul_f32_e32 v1, v1, v73
	v_cndmask_b32_e64 v83, 0, v1, s[82:83]
	v_mul_f32_e32 v1, v15, v77
	v_mul_f32_e32 v1, v1, v79
	v_cndmask_b32_e64 v81, 0, v1, s[84:85]
	v_mul_f32_e32 v1, v15, v94
	v_mul_f32_e32 v1, v1, v99
	v_cndmask_b32_e64 v5, 0, v1, s[86:87]
	v_mul_f32_e32 v1, v15, v157
	v_mul_f32_e32 v1, v1, v158
	v_cndmask_b32_e64 v79, 0, v1, s[88:89]
	v_mul_f32_e32 v1, v15, v159
	v_mul_f32_e32 v1, v1, v160
	v_cndmask_b32_e64 v77, 0, v1, s[90:91]
	v_mul_f32_e32 v1, v15, v161
	v_mul_f32_e32 v1, v1, v162
	v_cndmask_b32_e64 v75, 0, v1, s[92:93]
	v_mul_f32_e32 v1, v15, v163
	v_mul_f32_e32 v1, v1, v164
	v_cndmask_b32_e64 v7, 0, v1, s[94:95]
	v_mul_f32_e32 v1, v15, v165
	v_mul_f32_e32 v1, v1, v166
	v_cndmask_b32_e64 v73, 0, v1, s[96:97]
	v_mul_f32_e32 v1, v15, v167
	v_mul_f32_e32 v1, v1, v168
	v_cndmask_b32_e64 v71, 0, v1, s[0:1]
	v_mul_f32_e32 v1, v15, v169
	v_mul_f32_e32 v1, v1, v170
	v_cndmask_b32_e64 v69, 0, v1, s[6:7]
	v_mul_f32_e32 v1, v15, v171
	v_mul_f32_e32 v1, v1, v172
	v_cndmask_b32_e64 v9, 0, v1, s[8:9]
	v_mul_f32_e32 v1, v15, v173
	v_mul_f32_e32 v1, v1, v174
	v_cndmask_b32_e64 v67, 0, v1, s[10:11]
	v_mul_f32_e32 v1, v15, v175
	v_mul_f32_e32 v1, v1, v176
	v_cndmask_b32_e64 v55, 0, v1, s[12:13]
	v_mul_f32_e32 v1, v15, v177
	v_mul_f32_e32 v1, v1, v180
	v_cndmask_b32_e64 v53, 0, v1, s[14:15]
	v_mul_f32_e32 v1, v15, v181
	v_mul_f32_e32 v1, v1, v182
	v_cndmask_b32_e64 v11, 0, v1, s[16:17]
	v_mul_f32_e32 v1, v15, v183
	v_mul_f32_e32 v1, v1, v184
	v_cndmask_b32_e64 v51, 0, v1, s[18:19]
	v_mul_f32_e32 v1, v15, v185
	v_mul_f32_e32 v1, v1, v186
	v_cndmask_b32_e64 v31, 0, v1, s[20:21]
	v_mul_f32_e32 v1, v15, v187
	v_mul_f32_e32 v1, v1, v188
	v_cndmask_b32_e64 v29, 0, v1, s[22:23]
	v_mul_f32_e32 v1, v15, v189
	v_mul_f32_e32 v1, v1, v190
	v_cndmask_b32_e64 v13, 0, v1, s[24:25]
	v_mul_f32_e32 v1, v15, v191
	v_mul_f32_e32 v1, v1, v192
	v_cndmask_b32_e64 v27, 0, v1, s[26:27]
	v_mul_f32_e32 v1, v15, v193
	v_mul_f32_e32 v1, v1, v194
	v_cndmask_b32_e64 v25, 0, v1, s[28:29]
	v_mul_f32_e32 v1, v15, v195
	v_mul_f32_e32 v1, v1, v196
	v_cndmask_b32_e64 v23, 0, v1, s[30:31]
	v_mul_f32_e32 v1, v15, v197
	v_mul_f32_e32 v1, v1, v198
	v_cndmask_b32_e64 v21, 0, v1, s[34:35]
	v_mul_f32_e32 v1, v15, v199
	v_mul_f32_e32 v1, v1, v200
	v_cndmask_b32_e64 v19, 0, v1, s[36:37]
	v_mul_f32_e32 v1, v15, v201
	v_mul_f32_e32 v1, v1, v202
	v_cndmask_b32_e32 v17, 0, v1, vcc
	v_ashrrev_i32_e32 v1, 31, v0
	s_waitcnt lgkmcnt(0)
	v_mov_b32_e32 v99, v96
	v_mov_b32_e32 v15, v97
	v_lshlrev_b64 v[96:97], 9, v[0:1]
	v_or3_b32 v97, v97, 0, 0
	v_or3_b32 v96, v96, s67, v56
	v_readlane_b32 s0, v237, 33
	v_readlane_b32 s2, v237, 29
	v_lshlrev_b64 v[96:97], 1, v[96:97]
	v_readlane_b32 s1, v237, 34
	v_readlane_b32 s3, v237, 30
	v_pk_add_f32 v[14:15], v[98:99], v[14:15]
	v_lshl_add_u64 v[98:99], s[0:1], 0, v[96:97]
	v_lshl_add_u64 v[96:97], s[2:3], 0, v[96:97]
	global_load_ushort v218, v[98:99], off nt
	global_load_ushort v214, v[96:97], off nt
	v_or_b32_e32 v96, 1, v0
	v_ashrrev_i32_e32 v97, 31, v96
	v_lshlrev_b64 v[96:97], 9, v[96:97]
	v_or3_b32 v97, v97, 0, 0
	v_or3_b32 v96, v96, s67, v56
	v_lshlrev_b64 v[96:97], 1, v[96:97]
	v_lshl_add_u64 v[98:99], s[0:1], 0, v[96:97]
	v_lshl_add_u64 v[96:97], s[2:3], 0, v[96:97]
	global_load_ushort v217, v[98:99], off nt
	global_load_ushort v216, v[96:97], off nt
	v_or_b32_e32 v96, 2, v0
	v_ashrrev_i32_e32 v97, 31, v96
	v_lshlrev_b64 v[96:97], 9, v[96:97]
	v_or3_b32 v97, v97, 0, 0
	v_or3_b32 v96, v96, s67, v56
	v_lshlrev_b64 v[96:97], 1, v[96:97]
	v_lshl_add_u64 v[98:99], s[0:1], 0, v[96:97]
	v_lshl_add_u64 v[96:97], s[2:3], 0, v[96:97]
	global_load_ushort v215, v[98:99], off nt
	global_load_ushort v1, v[96:97], off nt
	v_or_b32_e32 v96, 3, v0
	v_ashrrev_i32_e32 v97, 31, v96
	v_lshlrev_b64 v[96:97], 9, v[96:97]
	v_or3_b32 v97, v97, 0, 0
	v_or3_b32 v96, v96, s67, v56
	v_lshlrev_b64 v[96:97], 1, v[96:97]
	v_lshl_add_u64 v[98:99], s[0:1], 0, v[96:97]
	v_lshl_add_u64 v[96:97], s[2:3], 0, v[96:97]
	global_load_ushort v213, v[98:99], off nt
	global_load_ushort v212, v[96:97], off nt
	v_or_b32_e32 v96, 4, v0
	v_ashrrev_i32_e32 v97, 31, v96
	v_lshlrev_b64 v[96:97], 9, v[96:97]
	v_or3_b32 v97, v97, 0, 0
	v_or3_b32 v96, v96, s67, v56
	v_lshlrev_b64 v[96:97], 1, v[96:97]
	v_lshl_add_u64 v[98:99], s[0:1], 0, v[96:97]
	v_lshl_add_u64 v[96:97], s[2:3], 0, v[96:97]
	global_load_ushort v211, v[98:99], off nt
	global_load_ushort v207, v[96:97], off nt
	v_or_b32_e32 v96, 5, v0
	v_ashrrev_i32_e32 v97, 31, v96
	v_lshlrev_b64 v[96:97], 9, v[96:97]
	v_or3_b32 v97, v97, 0, 0
	v_or3_b32 v96, v96, s67, v56
	v_lshlrev_b64 v[96:97], 1, v[96:97]
	v_lshl_add_u64 v[98:99], s[0:1], 0, v[96:97]
	v_lshl_add_u64 v[96:97], s[2:3], 0, v[96:97]
	global_load_ushort v210, v[98:99], off nt
	global_load_ushort v209, v[96:97], off nt
	v_or_b32_e32 v96, 6, v0
	v_ashrrev_i32_e32 v97, 31, v96
	v_lshlrev_b64 v[96:97], 9, v[96:97]
	v_or3_b32 v97, v97, 0, 0
	v_or3_b32 v96, v96, s67, v56
; __global__ void __launch_bounds__(NT, 2) hymba_fwd(Args args) {
;     ...
;             for (int i = 0; i < 32; ++i) { const size_t g = (size_t)(rbase + 32 * seg + i) * 512 + h * 128 + d; qr[i] = __builtin_nontemporal_load(QH + g); vr[i] = __builtin_nontemporal_load(VH + g); }
	v_lshlrev_b64 v[96:97], 1, v[96:97]
	v_lshl_add_u64 v[98:99], s[0:1], 0, v[96:97]
	v_lshl_add_u64 v[96:97], s[2:3], 0, v[96:97]
	global_load_ushort v208, v[98:99], off nt
	global_load_ushort v203, v[96:97], off nt
	v_or_b32_e32 v96, 7, v0
	v_ashrrev_i32_e32 v97, 31, v96
	v_lshlrev_b64 v[96:97], 9, v[96:97]
	v_or3_b32 v97, v97, 0, 0
	v_or3_b32 v96, v96, s67, v56
	v_lshlrev_b64 v[96:97], 1, v[96:97]
	v_lshl_add_u64 v[98:99], s[0:1], 0, v[96:97]
	v_lshl_add_u64 v[96:97], s[2:3], 0, v[96:97]
	global_load_ushort v206, v[98:99], off nt
	global_load_ushort v205, v[96:97], off nt
	v_or_b32_e32 v96, 8, v0
	v_ashrrev_i32_e32 v97, 31, v96
	v_lshlrev_b64 v[96:97], 9, v[96:97]
	v_or3_b32 v97, v97, 0, 0
	v_or3_b32 v96, v96, s67, v56
	v_lshlrev_b64 v[96:97], 1, v[96:97]
	v_lshl_add_u64 v[98:99], s[0:1], 0, v[96:97]
	v_lshl_add_u64 v[96:97], s[2:3], 0, v[96:97]
	global_load_ushort v204, v[98:99], off nt
	global_load_ushort v199, v[96:97], off nt
	v_or_b32_e32 v96, 9, v0
	v_ashrrev_i32_e32 v97, 31, v96
	v_lshlrev_b64 v[96:97], 9, v[96:97]
	v_or3_b32 v97, v97, 0, 0
	v_or3_b32 v96, v96, s67, v56
	v_lshlrev_b64 v[96:97], 1, v[96:97]
	v_lshl_add_u64 v[98:99], s[0:1], 0, v[96:97]
	v_lshl_add_u64 v[96:97], s[2:3], 0, v[96:97]
	global_load_ushort v202, v[98:99], off nt
	global_load_ushort v201, v[96:97], off nt
	v_or_b32_e32 v96, 10, v0
	v_ashrrev_i32_e32 v97, 31, v96
	v_lshlrev_b64 v[96:97], 9, v[96:97]
	v_or3_b32 v97, v97, 0, 0
	v_or3_b32 v96, v96, s67, v56
	v_lshlrev_b64 v[96:97], 1, v[96:97]
	v_lshl_add_u64 v[98:99], s[0:1], 0, v[96:97]
	v_lshl_add_u64 v[96:97], s[2:3], 0, v[96:97]
	global_load_ushort v200, v[98:99], off nt
	global_load_ushort v195, v[96:97], off nt
	v_or_b32_e32 v96, 11, v0
	v_ashrrev_i32_e32 v97, 31, v96
	v_lshlrev_b64 v[96:97], 9, v[96:97]
	v_or3_b32 v97, v97, 0, 0
	v_or3_b32 v96, v96, s67, v56
	v_lshlrev_b64 v[96:97], 1, v[96:97]
	v_lshl_add_u64 v[98:99], s[0:1], 0, v[96:97]
	v_lshl_add_u64 v[96:97], s[2:3], 0, v[96:97]
	global_load_ushort v198, v[98:99], off nt
	global_load_ushort v197, v[96:97], off nt
	v_or_b32_e32 v96, 12, v0
	v_ashrrev_i32_e32 v97, 31, v96
	v_lshlrev_b64 v[96:97], 9, v[96:97]
	v_or3_b32 v97, v97, 0, 0
	v_or3_b32 v96, v96, s67, v56
	v_lshlrev_b64 v[96:97], 1, v[96:97]
	v_lshl_add_u64 v[98:99], s[0:1], 0, v[96:97]
	v_lshl_add_u64 v[96:97], s[2:3], 0, v[96:97]
	global_load_ushort v196, v[98:99], off nt
	global_load_ushort v191, v[96:97], off nt
	v_or_b32_e32 v96, 13, v0
	v_ashrrev_i32_e32 v97, 31, v96
	v_lshlrev_b64 v[96:97], 9, v[96:97]
	v_or3_b32 v97, v97, 0, 0
	v_or3_b32 v96, v96, s67, v56
	v_lshlrev_b64 v[96:97], 1, v[96:97]
	v_lshl_add_u64 v[98:99], s[0:1], 0, v[96:97]
	v_lshl_add_u64 v[96:97], s[2:3], 0, v[96:97]
	global_load_ushort v194, v[98:99], off nt
	global_load_ushort v193, v[96:97], off nt
	v_or_b32_e32 v96, 14, v0
	v_ashrrev_i32_e32 v97, 31, v96
	v_lshlrev_b64 v[96:97], 9, v[96:97]
	v_or3_b32 v97, v97, 0, 0
	v_or3_b32 v96, v96, s67, v56
	v_lshlrev_b64 v[96:97], 1, v[96:97]
	v_lshl_add_u64 v[98:99], s[0:1], 0, v[96:97]
	v_lshl_add_u64 v[96:97], s[2:3], 0, v[96:97]
	global_load_ushort v192, v[98:99], off nt
	global_load_ushort v187, v[96:97], off nt
	v_or_b32_e32 v96, 15, v0
	v_ashrrev_i32_e32 v97, 31, v96
	v_lshlrev_b64 v[96:97], 9, v[96:97]
	v_or3_b32 v97, v97, 0, 0
	v_or3_b32 v96, v96, s67, v56
	v_lshlrev_b64 v[96:97], 1, v[96:97]
	v_lshl_add_u64 v[98:99], s[0:1], 0, v[96:97]
	v_lshl_add_u64 v[96:97], s[2:3], 0, v[96:97]
	global_load_ushort v190, v[98:99], off nt
	global_load_ushort v189, v[96:97], off nt
	v_or_b32_e32 v96, 16, v0
	v_ashrrev_i32_e32 v97, 31, v96
	v_lshlrev_b64 v[96:97], 9, v[96:97]
	v_or3_b32 v97, v97, 0, 0
	v_or3_b32 v96, v96, s67, v56
	v_lshlrev_b64 v[96:97], 1, v[96:97]
	v_lshl_add_u64 v[98:99], s[0:1], 0, v[96:97]
	v_lshl_add_u64 v[96:97], s[2:3], 0, v[96:97]
	global_load_ushort v188, v[98:99], off nt
	global_load_ushort v183, v[96:97], off nt
	v_or_b32_e32 v96, 17, v0
	v_ashrrev_i32_e32 v97, 31, v96
	v_lshlrev_b64 v[96:97], 9, v[96:97]
	v_or3_b32 v97, v97, 0, 0
	v_or3_b32 v96, v96, s67, v56
	v_lshlrev_b64 v[96:97], 1, v[96:97]
	v_lshl_add_u64 v[98:99], s[0:1], 0, v[96:97]
	v_lshl_add_u64 v[96:97], s[2:3], 0, v[96:97]
	global_load_ushort v186, v[98:99], off nt
	global_load_ushort v185, v[96:97], off nt
	v_or_b32_e32 v96, 18, v0
	v_ashrrev_i32_e32 v97, 31, v96
	v_lshlrev_b64 v[96:97], 9, v[96:97]
	v_or3_b32 v97, v97, 0, 0
	v_or3_b32 v96, v96, s67, v56
	v_lshlrev_b64 v[96:97], 1, v[96:97]
	v_lshl_add_u64 v[98:99], s[0:1], 0, v[96:97]
	v_lshl_add_u64 v[96:97], s[2:3], 0, v[96:97]
	global_load_ushort v184, v[98:99], off nt
	global_load_ushort v177, v[96:97], off nt
	v_or_b32_e32 v96, 19, v0
	v_ashrrev_i32_e32 v97, 31, v96
	v_lshlrev_b64 v[96:97], 9, v[96:97]
	v_or3_b32 v97, v97, 0, 0
	v_or3_b32 v96, v96, s67, v56
	v_lshlrev_b64 v[96:97], 1, v[96:97]
	v_lshl_add_u64 v[98:99], s[0:1], 0, v[96:97]
	v_lshl_add_u64 v[96:97], s[2:3], 0, v[96:97]
	global_load_ushort v182, v[98:99], off nt
	global_load_ushort v181, v[96:97], off nt
	v_or_b32_e32 v96, 20, v0
	v_ashrrev_i32_e32 v97, 31, v96
	v_lshlrev_b64 v[96:97], 9, v[96:97]
	v_or3_b32 v97, v97, 0, 0
	v_or3_b32 v96, v96, s67, v56
	v_lshlrev_b64 v[96:97], 1, v[96:97]
	v_lshl_add_u64 v[98:99], s[0:1], 0, v[96:97]
	v_lshl_add_u64 v[96:97], s[2:3], 0, v[96:97]
	global_load_ushort v180, v[98:99], off nt
	global_load_ushort v173, v[96:97], off nt
	v_or_b32_e32 v96, 21, v0
	v_ashrrev_i32_e32 v97, 31, v96
	v_lshlrev_b64 v[96:97], 9, v[96:97]
	v_or3_b32 v97, v97, 0, 0
	v_or3_b32 v96, v96, s67, v56
	v_lshlrev_b64 v[96:97], 1, v[96:97]
	v_lshl_add_u64 v[98:99], s[0:1], 0, v[96:97]
	v_lshl_add_u64 v[96:97], s[2:3], 0, v[96:97]
	global_load_ushort v176, v[98:99], off nt
; __device__ __forceinline__ unsigned cvtpk_s(float lo, float hi) { f32x2_t v = {lo, hi}; bf16x2_t b = __builtin_convertvector(v, bf16x2_t); return __builtin_bit_cast(unsigned, b); }
; __global__ void __launch_bounds__(NT, 2) hymba_fwd(Args args) {
;     ...
;             for (int i = 0; i < 32; ++i) { const size_t g = (size_t)(rbase + 32 * seg + i) * 512 + h * 128 + d; qr[i] = __builtin_nontemporal_load(QH + g); vr[i] = __builtin_nontemporal_load(VH + g); }
; #pragma unroll
;             for (int i = 0; i < 32; ++i) { const int s = 32 * seg + i;
;                 run += lf[i]; const float q = bf2f((unsigned short)qr[i]);
;                 { const float e1 = __expf(fminf(fmaxf(run - ref, -80.f), 80.f)), qt = q * e1; const unsigned pa = cvtpk_s(qt, kk[i] * __builtin_amdgcn_rcpf(e1)), pb = cvtpk_s(qt * eref, 0.f); X0[s * XP + d] = (bf16)pa; X1[s * XP + d] = (bf16)(pa >> 16); X2[s * XP + d] = (bf16)pb; }
	global_load_ushort v175, v[96:97], off nt
	v_or_b32_e32 v96, 22, v0
	v_ashrrev_i32_e32 v97, 31, v96
	v_lshlrev_b64 v[96:97], 9, v[96:97]
	v_or3_b32 v97, v97, 0, 0
	v_or3_b32 v96, v96, s67, v56
	v_lshlrev_b64 v[96:97], 1, v[96:97]
	v_lshl_add_u64 v[98:99], s[0:1], 0, v[96:97]
	v_lshl_add_u64 v[96:97], s[2:3], 0, v[96:97]
	global_load_ushort v174, v[98:99], off nt
	global_load_ushort v169, v[96:97], off nt
	v_or_b32_e32 v96, 23, v0
	v_ashrrev_i32_e32 v97, 31, v96
	v_lshlrev_b64 v[96:97], 9, v[96:97]
	v_or3_b32 v97, v97, 0, 0
	v_or3_b32 v96, v96, s67, v56
	v_lshlrev_b64 v[96:97], 1, v[96:97]
	v_lshl_add_u64 v[98:99], s[0:1], 0, v[96:97]
	v_lshl_add_u64 v[96:97], s[2:3], 0, v[96:97]
	global_load_ushort v172, v[98:99], off nt
	global_load_ushort v171, v[96:97], off nt
	v_or_b32_e32 v96, 24, v0
	v_ashrrev_i32_e32 v97, 31, v96
	v_lshlrev_b64 v[96:97], 9, v[96:97]
	v_or3_b32 v97, v97, 0, 0
	v_or3_b32 v96, v96, s67, v56
	v_lshlrev_b64 v[96:97], 1, v[96:97]
	v_lshl_add_u64 v[98:99], s[0:1], 0, v[96:97]
	v_lshl_add_u64 v[96:97], s[2:3], 0, v[96:97]
	global_load_ushort v170, v[98:99], off nt
	global_load_ushort v165, v[96:97], off nt
	v_or_b32_e32 v96, 25, v0
	v_ashrrev_i32_e32 v97, 31, v96
	v_lshlrev_b64 v[96:97], 9, v[96:97]
	v_or3_b32 v97, v97, 0, 0
	v_or3_b32 v96, v96, s67, v56
	v_lshlrev_b64 v[96:97], 1, v[96:97]
	v_lshl_add_u64 v[98:99], s[0:1], 0, v[96:97]
	v_lshl_add_u64 v[96:97], s[2:3], 0, v[96:97]
	global_load_ushort v168, v[98:99], off nt
	global_load_ushort v167, v[96:97], off nt
	v_or_b32_e32 v96, 26, v0
	v_ashrrev_i32_e32 v97, 31, v96
	v_lshlrev_b64 v[96:97], 9, v[96:97]
	v_or3_b32 v97, v97, 0, 0
	v_or3_b32 v96, v96, s67, v56
	v_lshlrev_b64 v[96:97], 1, v[96:97]
	v_lshl_add_u64 v[98:99], s[0:1], 0, v[96:97]
	v_lshl_add_u64 v[96:97], s[2:3], 0, v[96:97]
	global_load_ushort v166, v[98:99], off nt
	global_load_ushort v161, v[96:97], off nt
	v_or_b32_e32 v96, 27, v0
	v_ashrrev_i32_e32 v97, 31, v96
	v_lshlrev_b64 v[96:97], 9, v[96:97]
	v_or3_b32 v97, v97, 0, 0
	v_or3_b32 v96, v96, s67, v56
	v_lshlrev_b64 v[96:97], 1, v[96:97]
	v_lshl_add_u64 v[98:99], s[0:1], 0, v[96:97]
	v_lshl_add_u64 v[96:97], s[2:3], 0, v[96:97]
	global_load_ushort v164, v[98:99], off nt
	global_load_ushort v163, v[96:97], off nt
	v_or_b32_e32 v96, 28, v0
	v_ashrrev_i32_e32 v97, 31, v96
	v_lshlrev_b64 v[96:97], 9, v[96:97]
	v_or3_b32 v97, v97, 0, 0
	v_or3_b32 v96, v96, s67, v56
	v_lshlrev_b64 v[96:97], 1, v[96:97]
	v_lshl_add_u64 v[98:99], s[0:1], 0, v[96:97]
	v_lshl_add_u64 v[96:97], s[2:3], 0, v[96:97]
	global_load_ushort v162, v[98:99], off nt
	global_load_ushort v157, v[96:97], off nt
	v_or_b32_e32 v96, 29, v0
	v_ashrrev_i32_e32 v97, 31, v96
	v_lshlrev_b64 v[96:97], 9, v[96:97]
	v_or3_b32 v97, v97, 0, 0
	v_or3_b32 v96, v96, s67, v56
	v_lshlrev_b64 v[96:97], 1, v[96:97]
	v_lshl_add_u64 v[98:99], s[0:1], 0, v[96:97]
	v_lshl_add_u64 v[96:97], s[2:3], 0, v[96:97]
	global_load_ushort v160, v[98:99], off nt
	global_load_ushort v159, v[96:97], off nt
	v_or_b32_e32 v96, 30, v0
	v_ashrrev_i32_e32 v97, 31, v96
	v_lshlrev_b64 v[96:97], 9, v[96:97]
	v_or3_b32 v97, v97, 0, 0
	v_or3_b32 v96, v96, s67, v56
	v_lshlrev_b64 v[96:97], 1, v[96:97]
	v_lshl_add_u64 v[98:99], s[0:1], 0, v[96:97]
	v_lshl_add_u64 v[96:97], s[2:3], 0, v[96:97]
	global_load_ushort v158, v[98:99], off nt
	v_mul_f32_e32 v94, 0x3fb8aa3b, v15
	global_load_ushort v96, v[96:97], off nt
	v_or_b32_e32 v98, 31, v0
	v_ashrrev_i32_e32 v99, 31, v98
	v_lshlrev_b64 v[98:99], 9, v[98:99]
	v_or3_b32 v99, v99, 0, 0
	v_or3_b32 v98, v98, s67, v56
	v_sub_f32_e32 v0, v14, v15
	v_lshlrev_b64 v[220:221], 1, v[98:99]
	v_med3_f32 v0, v0, s63, v152
	v_lshl_add_u64 v[98:99], s[0:1], 0, v[220:221]
	v_lshl_add_u64 v[220:221], s[2:3], 0, v[220:221]
	v_mul_f32_e32 v0, 0x3fb8aa3b, v0
	global_load_ushort v99, v[98:99], off nt
	s_waitcnt vmcnt(62)
	v_lshlrev_b32_e32 v218, 16, v218
	global_load_ushort v97, v[220:221], off nt
	v_exp_f32_e32 v98, v94
	v_exp_f32_e32 v94, v0
	v_add_f32_e32 v14, v14, v92
	s_waitcnt vmcnt(56)
	v_lshl_or_b32 v1, v212, 16, v1
	v_rcp_f32_e32 v219, v94
	s_nop 0
	v_pk_mul_f32 v[94:95], v[94:95], v[218:219]
	s_nop 0
	v_cvt_pk_bf16_f32 v0, v94, v95
	v_mul_f32_e32 v94, v98, v94
	v_cvt_pk_bf16_f32 v94, v94, s0
	ds_write_b16 v106, v0
	ds_write_b16_d16_hi v106, v0 offset:34816
	ds_write_b16 v107, v94
	v_sub_f32_e32 v0, v14, v15
	v_med3_f32 v0, v0, s63, v152
	v_mul_f32_e32 v0, 0x3fb8aa3b, v0
	v_exp_f32_e32 v92, v0
	v_add_f32_e32 v14, v14, v90
	v_sub_f32_e32 v90, v14, v15
	v_med3_f32 v90, v90, s63, v152
	v_rcp_f32_e32 v95, v92
	v_mul_f32_e32 v90, 0x3fb8aa3b, v90
	v_exp_f32_e32 v90, v90
	v_lshlrev_b32_e32 v94, 16, v217
	v_add_f32_e32 v14, v14, v88
	v_pk_mul_f32 v[92:93], v[92:93], v[94:95]
	v_sub_f32_e32 v88, v14, v15
	v_cvt_pk_bf16_f32 v0, v92, v93
	v_rcp_f32_e32 v93, v90
	v_med3_f32 v88, v88, s63, v152
	v_mul_f32_e32 v92, v98, v92
	v_mul_f32_e32 v88, 0x3fb8aa3b, v88
	v_cvt_pk_bf16_f32 v92, v92, s0
	v_exp_f32_e32 v88, v88
	ds_write_b16 v106, v0 offset:272
	ds_write_b16_d16_hi v106, v0 offset:35088
	ds_write_b16 v108, v92
	v_lshlrev_b32_e32 v92, 16, v215
	v_pk_mul_f32 v[90:91], v[90:91], v[92:93]
	v_add_f32_e32 v14, v14, v86
	v_cvt_pk_bf16_f32 v91, v90, v91
	v_mul_f32_e32 v90, v98, v90
	v_sub_f32_e32 v86, v14, v15
	v_cvt_pk_bf16_f32 v90, v90, s0
	ds_write_b16 v106, v91 offset:544
	ds_write_b16_d16_hi v106, v91 offset:35360
	ds_write_b16 v109, v90
	v_rcp_f32_e32 v91, v88
	v_med3_f32 v86, v86, s63, v152
	v_mul_f32_e32 v86, 0x3fb8aa3b, v86
	v_exp_f32_e32 v86, v86
	v_lshlrev_b32_e32 v90, 16, v213
	v_pk_mul_f32 v[88:89], v[88:89], v[90:91]
	v_add_f32_e32 v14, v14, v2
	v_cvt_pk_bf16_f32 v89, v88, v89
	v_mul_f32_e32 v88, v98, v88
	v_sub_f32_e32 v2, v14, v15
	v_cvt_pk_bf16_f32 v88, v88, s0
	ds_write_b16 v106, v89 offset:816
	ds_write_b16_d16_hi v106, v89 offset:35632
	ds_write_b16 v110, v88
	v_rcp_f32_e32 v89, v86
	v_med3_f32 v2, v2, s63, v152
	v_mul_f32_e32 v2, 0x3fb8aa3b, v2
	v_exp_f32_e32 v2, v2
	s_waitcnt vmcnt(55)
; __device__ __forceinline__ unsigned cvtpk_s(float lo, float hi) { f32x2_t v = {lo, hi}; bf16x2_t b = __builtin_convertvector(v, bf16x2_t); return __builtin_bit_cast(unsigned, b); }
; __global__ void __launch_bounds__(NT, 2) hymba_fwd(Args args) {
;     ...
;             for (int i = 0; i < 32; ++i) { const int s = 32 * seg + i;
;                 run += lf[i]; const float q = bf2f((unsigned short)qr[i]);
;                 { const float e1 = __expf(fminf(fmaxf(run - ref, -80.f), 80.f)), qt = q * e1; const unsigned pa = cvtpk_s(qt, kk[i] * __builtin_amdgcn_rcpf(e1)), pb = cvtpk_s(qt * eref, 0.f); X0[s * XP + d] = (bf16)pa; X1[s * XP + d] = (bf16)(pa >> 16); X2[s * XP + d] = (bf16)pb; }
;                 const unsigned v = vr[i]; if (i & 1) vp[i >> 1] |= v << 16; else vp[i >> 1] = v; }
	v_lshlrev_b32_e32 v88, 16, v211
	v_pk_mul_f32 v[86:87], v[86:87], v[88:89]
	v_lshl_or_b32 v0, v216, 16, v214
	v_cvt_pk_bf16_f32 v87, v86, v87
	v_mul_f32_e32 v86, v98, v86
	v_cvt_pk_bf16_f32 v86, v86, s0
	ds_write_b16 v106, v87 offset:1088
	ds_write_b16_d16_hi v106, v87 offset:35904
	ds_write_b16 v111, v86
	v_rcp_f32_e32 v87, v2
	s_waitcnt vmcnt(53)
	v_lshlrev_b32_e32 v86, 16, v210
	v_pk_mul_f32 v[2:3], v[2:3], v[86:87]
	s_nop 0
	v_cvt_pk_bf16_f32 v3, v2, v3
	v_mul_f32_e32 v2, v98, v2
	v_cvt_pk_bf16_f32 v2, v2, s0
	ds_write_b16 v106, v3 offset:1360
	ds_write_b16_d16_hi v106, v3 offset:36176
	ds_write_b16 v112, v2
	v_add_f32_e32 v3, v14, v84
	v_sub_f32_e32 v14, v3, v15
	v_med3_f32 v14, v14, s63, v152
	v_mul_f32_e32 v14, 0x3fb8aa3b, v14
	v_exp_f32_e32 v84, v14
	s_waitcnt vmcnt(51)
	v_lshlrev_b32_e32 v86, 16, v208
	v_lshl_or_b32 v2, v209, 16, v207
	v_rcp_f32_e32 v87, v84
	s_nop 0
	v_pk_mul_f32 v[84:85], v[84:85], v[86:87]
	s_nop 0
	v_cvt_pk_bf16_f32 v14, v84, v85
	v_mul_f32_e32 v84, v98, v84
	v_cvt_pk_bf16_f32 v84, v84, s0
	ds_write_b16 v106, v14 offset:1632
	ds_write_b16_d16_hi v106, v14 offset:36448
	ds_write_b16 v113, v84
	v_add_f32_e32 v14, v3, v82
	v_sub_f32_e32 v3, v14, v15
	v_med3_f32 v3, v3, s63, v152
	v_mul_f32_e32 v3, 0x3fb8aa3b, v3
	v_exp_f32_e32 v82, v3
	v_add_f32_e32 v14, v14, v80
	v_sub_f32_e32 v80, v14, v15
	v_med3_f32 v80, v80, s63, v152
	v_rcp_f32_e32 v85, v82
	v_mul_f32_e32 v80, 0x3fb8aa3b, v80
	v_exp_f32_e32 v80, v80
	s_waitcnt vmcnt(49)
	v_lshlrev_b32_e32 v84, 16, v206
	v_add_f32_e32 v14, v14, v4
	v_pk_mul_f32 v[82:83], v[82:83], v[84:85]
	v_sub_f32_e32 v4, v14, v15
	v_cvt_pk_bf16_f32 v3, v82, v83
	v_rcp_f32_e32 v83, v80
	v_med3_f32 v4, v4, s63, v152
	v_mul_f32_e32 v82, v98, v82
	v_mul_f32_e32 v4, 0x3fb8aa3b, v4
	v_cvt_pk_bf16_f32 v82, v82, s0
	v_exp_f32_e32 v4, v4
	ds_write_b16 v106, v3 offset:1904
	ds_write_b16_d16_hi v106, v3 offset:36720
	ds_write_b16 v114, v82
	s_waitcnt vmcnt(47)
	v_lshlrev_b32_e32 v82, 16, v204
	v_pk_mul_f32 v[80:81], v[80:81], v[82:83]
	v_lshl_or_b32 v3, v205, 16, v203
	v_cvt_pk_bf16_f32 v81, v80, v81
	v_mul_f32_e32 v80, v98, v80
	v_cvt_pk_bf16_f32 v80, v80, s0
	ds_write_b16 v106, v81 offset:2176
	ds_write_b16_d16_hi v106, v81 offset:36992
	ds_write_b16 v115, v80
	v_rcp_f32_e32 v81, v4
	s_waitcnt vmcnt(45)
	v_lshlrev_b32_e32 v80, 16, v202
	v_pk_mul_f32 v[4:5], v[4:5], v[80:81]
	s_nop 0
	v_cvt_pk_bf16_f32 v5, v4, v5
	v_mul_f32_e32 v4, v98, v4
	v_cvt_pk_bf16_f32 v4, v4, s0
	ds_write_b16 v106, v5 offset:2448
	ds_write_b16_d16_hi v106, v5 offset:37264
	ds_write_b16 v116, v4
	v_add_f32_e32 v5, v14, v78
	v_sub_f32_e32 v14, v5, v15
	v_med3_f32 v14, v14, s63, v152
	v_mul_f32_e32 v14, 0x3fb8aa3b, v14
	v_exp_f32_e32 v78, v14
	s_waitcnt vmcnt(43)
	v_lshlrev_b32_e32 v80, 16, v200
	v_lshl_or_b32 v4, v201, 16, v199
	v_rcp_f32_e32 v81, v78
	s_nop 0
	v_pk_mul_f32 v[78:79], v[78:79], v[80:81]
	s_nop 0
	v_cvt_pk_bf16_f32 v14, v78, v79
	v_mul_f32_e32 v78, v98, v78
	v_cvt_pk_bf16_f32 v78, v78, s0
	ds_write_b16 v106, v14 offset:2720
	ds_write_b16_d16_hi v106, v14 offset:37536
	ds_write_b16 v117, v78
	v_add_f32_e32 v14, v5, v76
	v_sub_f32_e32 v5, v14, v15
	v_med3_f32 v5, v5, s63, v152
	v_mul_f32_e32 v5, 0x3fb8aa3b, v5
	v_exp_f32_e32 v76, v5
	v_add_f32_e32 v14, v14, v74
	v_sub_f32_e32 v74, v14, v15
	v_med3_f32 v74, v74, s63, v152
	v_rcp_f32_e32 v79, v76
	v_mul_f32_e32 v74, 0x3fb8aa3b, v74
	v_exp_f32_e32 v74, v74
	s_waitcnt vmcnt(41)
	v_lshlrev_b32_e32 v78, 16, v198
	v_add_f32_e32 v14, v14, v6
	v_pk_mul_f32 v[76:77], v[76:77], v[78:79]
	v_sub_f32_e32 v6, v14, v15
	v_cvt_pk_bf16_f32 v5, v76, v77
	v_rcp_f32_e32 v77, v74
	v_med3_f32 v6, v6, s63, v152
	v_mul_f32_e32 v76, v98, v76
	v_mul_f32_e32 v6, 0x3fb8aa3b, v6
	v_cvt_pk_bf16_f32 v76, v76, s0
	v_exp_f32_e32 v6, v6
	ds_write_b16 v106, v5 offset:2992
	ds_write_b16_d16_hi v106, v5 offset:37808
	ds_write_b16 v118, v76
	s_waitcnt vmcnt(39)
	v_lshlrev_b32_e32 v76, 16, v196
	v_pk_mul_f32 v[74:75], v[74:75], v[76:77]
	v_lshl_or_b32 v5, v197, 16, v195
	v_cvt_pk_bf16_f32 v75, v74, v75
	v_mul_f32_e32 v74, v98, v74
	v_cvt_pk_bf16_f32 v74, v74, s0
	ds_write_b16 v106, v75 offset:3264
	ds_write_b16_d16_hi v106, v75 offset:38080
	ds_write_b16 v119, v74
	v_rcp_f32_e32 v75, v6
	s_waitcnt vmcnt(37)
	v_lshlrev_b32_e32 v74, 16, v194
	v_pk_mul_f32 v[6:7], v[6:7], v[74:75]
	s_nop 0
	v_cvt_pk_bf16_f32 v7, v6, v7
	v_mul_f32_e32 v6, v98, v6
	v_cvt_pk_bf16_f32 v6, v6, s0
	ds_write_b16 v106, v7 offset:3536
	ds_write_b16_d16_hi v106, v7 offset:38352
	ds_write_b16 v120, v6
	v_add_f32_e32 v7, v14, v72
	v_sub_f32_e32 v14, v7, v15
	v_med3_f32 v14, v14, s63, v152
	v_mul_f32_e32 v14, 0x3fb8aa3b, v14
	v_exp_f32_e32 v72, v14
	s_waitcnt vmcnt(35)
	v_lshlrev_b32_e32 v74, 16, v192
	v_lshl_or_b32 v6, v193, 16, v191
	v_rcp_f32_e32 v75, v72
	s_nop 0
	v_pk_mul_f32 v[72:73], v[72:73], v[74:75]
	s_nop 0
	v_cvt_pk_bf16_f32 v14, v72, v73
	v_mul_f32_e32 v72, v98, v72
	v_cvt_pk_bf16_f32 v72, v72, s0
	ds_write_b16 v106, v14 offset:3808
	ds_write_b16_d16_hi v106, v14 offset:38624
	ds_write_b16 v121, v72
	v_add_f32_e32 v14, v7, v70
	v_sub_f32_e32 v7, v14, v15
	v_med3_f32 v7, v7, s63, v152
	v_mul_f32_e32 v7, 0x3fb8aa3b, v7
	v_exp_f32_e32 v70, v7
	v_add_f32_e32 v14, v14, v68
	v_sub_f32_e32 v68, v14, v15
	v_med3_f32 v68, v68, s63, v152
	v_rcp_f32_e32 v73, v70
	v_mul_f32_e32 v68, 0x3fb8aa3b, v68
	v_exp_f32_e32 v68, v68
	s_waitcnt vmcnt(33)
	v_lshlrev_b32_e32 v72, 16, v190
	v_add_f32_e32 v14, v14, v8
	v_pk_mul_f32 v[70:71], v[70:71], v[72:73]
	v_sub_f32_e32 v8, v14, v15
	v_cvt_pk_bf16_f32 v7, v70, v71
	v_rcp_f32_e32 v71, v68
	v_med3_f32 v8, v8, s63, v152
	v_mul_f32_e32 v70, v98, v70
	v_mul_f32_e32 v8, 0x3fb8aa3b, v8
	v_cvt_pk_bf16_f32 v70, v70, s0
	v_exp_f32_e32 v8, v8
	ds_write_b16 v106, v7 offset:4080
	ds_write_b16_d16_hi v106, v7 offset:38896
	ds_write_b16 v122, v70
	s_waitcnt vmcnt(31)
; __device__ __forceinline__ unsigned cvtpk_s(float lo, float hi) { f32x2_t v = {lo, hi}; bf16x2_t b = __builtin_convertvector(v, bf16x2_t); return __builtin_bit_cast(unsigned, b); }
; __global__ void __launch_bounds__(NT, 2) hymba_fwd(Args args) {
;     ...
;             for (int i = 0; i < 32; ++i) { const int s = 32 * seg + i;
;                 run += lf[i]; const float q = bf2f((unsigned short)qr[i]);
;                 { const float e1 = __expf(fminf(fmaxf(run - ref, -80.f), 80.f)), qt = q * e1; const unsigned pa = cvtpk_s(qt, kk[i] * __builtin_amdgcn_rcpf(e1)), pb = cvtpk_s(qt * eref, 0.f); X0[s * XP + d] = (bf16)pa; X1[s * XP + d] = (bf16)(pa >> 16); X2[s * XP + d] = (bf16)pb; }
;                 const unsigned v = vr[i]; if (i & 1) vp[i >> 1] |= v << 16; else vp[i >> 1] = v; }
	v_lshlrev_b32_e32 v70, 16, v188
	v_pk_mul_f32 v[68:69], v[68:69], v[70:71]
	v_lshl_or_b32 v7, v189, 16, v187
	v_cvt_pk_bf16_f32 v69, v68, v69
	v_mul_f32_e32 v68, v98, v68
	v_cvt_pk_bf16_f32 v68, v68, s0
	ds_write_b16 v106, v69 offset:4352
	ds_write_b16_d16_hi v106, v69 offset:39168
	ds_write_b16 v123, v68
	v_rcp_f32_e32 v69, v8
	s_waitcnt vmcnt(29)
	v_lshlrev_b32_e32 v68, 16, v186
	v_pk_mul_f32 v[8:9], v[8:9], v[68:69]
	s_nop 0
	v_cvt_pk_bf16_f32 v9, v8, v9
	v_mul_f32_e32 v8, v98, v8
	v_cvt_pk_bf16_f32 v8, v8, s0
	ds_write_b16 v106, v9 offset:4624
	ds_write_b16_d16_hi v106, v9 offset:39440
	ds_write_b16 v124, v8
	v_add_f32_e32 v9, v14, v66
	v_sub_f32_e32 v14, v9, v15
	v_med3_f32 v14, v14, s63, v152
	v_mul_f32_e32 v14, 0x3fb8aa3b, v14
	v_exp_f32_e32 v66, v14
	s_waitcnt vmcnt(27)
	v_lshlrev_b32_e32 v68, 16, v184
	v_lshl_or_b32 v8, v185, 16, v183
	v_rcp_f32_e32 v69, v66
	s_nop 0
	v_pk_mul_f32 v[66:67], v[66:67], v[68:69]
	s_nop 0
	v_cvt_pk_bf16_f32 v14, v66, v67
	v_mul_f32_e32 v66, v98, v66
	v_cvt_pk_bf16_f32 v66, v66, s0
	ds_write_b16 v106, v14 offset:4896
	ds_write_b16_d16_hi v106, v14 offset:39712
	ds_write_b16 v125, v66
	v_add_f32_e32 v14, v9, v54
	v_sub_f32_e32 v9, v14, v15
	v_med3_f32 v9, v9, s63, v152
	v_mul_f32_e32 v9, 0x3fb8aa3b, v9
	v_exp_f32_e32 v54, v9
	v_add_f32_e32 v14, v14, v52
	v_sub_f32_e32 v52, v14, v15
	v_med3_f32 v52, v52, s63, v152
	v_rcp_f32_e32 v67, v54
	v_mul_f32_e32 v52, 0x3fb8aa3b, v52
	v_exp_f32_e32 v52, v52
	s_waitcnt vmcnt(25)
	v_lshlrev_b32_e32 v66, 16, v182
	v_add_f32_e32 v14, v14, v10
	v_pk_mul_f32 v[54:55], v[54:55], v[66:67]
	v_sub_f32_e32 v10, v14, v15
	v_cvt_pk_bf16_f32 v9, v54, v55
	v_rcp_f32_e32 v55, v52
	v_med3_f32 v10, v10, s63, v152
	v_mul_f32_e32 v54, v98, v54
	v_mul_f32_e32 v10, 0x3fb8aa3b, v10
	v_cvt_pk_bf16_f32 v54, v54, s0
	v_exp_f32_e32 v10, v10
	ds_write_b16 v106, v9 offset:5168
	ds_write_b16_d16_hi v106, v9 offset:39984
	ds_write_b16 v126, v54
	s_waitcnt vmcnt(23)
	v_lshlrev_b32_e32 v54, 16, v180
	v_pk_mul_f32 v[52:53], v[52:53], v[54:55]
	v_lshl_or_b32 v9, v181, 16, v177
	v_cvt_pk_bf16_f32 v53, v52, v53
	v_mul_f32_e32 v52, v98, v52
	v_cvt_pk_bf16_f32 v52, v52, s0
	ds_write_b16 v106, v53 offset:5440
	ds_write_b16_d16_hi v106, v53 offset:40256
	ds_write_b16 v127, v52
	v_rcp_f32_e32 v53, v10
	s_waitcnt vmcnt(21)
	v_lshlrev_b32_e32 v52, 16, v176
	v_pk_mul_f32 v[10:11], v[10:11], v[52:53]
	s_nop 0
	v_cvt_pk_bf16_f32 v11, v10, v11
	v_mul_f32_e32 v10, v98, v10
	v_cvt_pk_bf16_f32 v10, v10, s0
	ds_write_b16 v106, v11 offset:5712
	ds_write_b16_d16_hi v106, v11 offset:40528
	ds_write_b16 v128, v10
	v_add_f32_e32 v11, v14, v50
	v_sub_f32_e32 v14, v11, v15
	v_med3_f32 v14, v14, s63, v152
	v_mul_f32_e32 v14, 0x3fb8aa3b, v14
	v_exp_f32_e32 v50, v14
	s_waitcnt vmcnt(19)
	v_lshlrev_b32_e32 v52, 16, v174
	v_lshl_or_b32 v10, v175, 16, v173
	v_rcp_f32_e32 v53, v50
	s_nop 0
	v_pk_mul_f32 v[50:51], v[50:51], v[52:53]
	s_nop 0
	v_cvt_pk_bf16_f32 v14, v50, v51
	v_mul_f32_e32 v50, v98, v50
	v_cvt_pk_bf16_f32 v50, v50, s0
	ds_write_b16 v106, v14 offset:5984
	ds_write_b16_d16_hi v106, v14 offset:40800
	ds_write_b16 v129, v50
	v_add_f32_e32 v14, v11, v30
	v_sub_f32_e32 v11, v14, v15
	v_med3_f32 v11, v11, s63, v152
	v_mul_f32_e32 v11, 0x3fb8aa3b, v11
	v_exp_f32_e32 v30, v11
	v_add_f32_e32 v14, v14, v28
	v_sub_f32_e32 v28, v14, v15
	v_med3_f32 v28, v28, s63, v152
	v_rcp_f32_e32 v51, v30
	v_mul_f32_e32 v28, 0x3fb8aa3b, v28
	v_exp_f32_e32 v28, v28
	s_waitcnt vmcnt(17)
	v_lshlrev_b32_e32 v50, 16, v172
	v_add_f32_e32 v14, v14, v12
	v_pk_mul_f32 v[30:31], v[30:31], v[50:51]
	v_sub_f32_e32 v12, v14, v15
	v_cvt_pk_bf16_f32 v11, v30, v31
	v_rcp_f32_e32 v31, v28
	v_med3_f32 v12, v12, s63, v152
	v_mul_f32_e32 v30, v98, v30
	v_mul_f32_e32 v12, 0x3fb8aa3b, v12
	v_cvt_pk_bf16_f32 v30, v30, s0
	v_exp_f32_e32 v12, v12
	ds_write_b16 v106, v11 offset:6256
	ds_write_b16_d16_hi v106, v11 offset:41072
	ds_write_b16 v130, v30
	s_waitcnt vmcnt(15)
	v_lshlrev_b32_e32 v30, 16, v170
	v_pk_mul_f32 v[28:29], v[28:29], v[30:31]
	v_lshl_or_b32 v11, v171, 16, v169
	v_cvt_pk_bf16_f32 v29, v28, v29
	v_mul_f32_e32 v28, v98, v28
	v_cvt_pk_bf16_f32 v28, v28, s0
	ds_write_b16 v106, v29 offset:6528
	ds_write_b16_d16_hi v106, v29 offset:41344
	ds_write_b16 v131, v28
	v_rcp_f32_e32 v29, v12
	s_waitcnt vmcnt(13)
	v_lshlrev_b32_e32 v28, 16, v168
	v_pk_mul_f32 v[12:13], v[12:13], v[28:29]
	s_nop 0
	v_cvt_pk_bf16_f32 v13, v12, v13
	v_mul_f32_e32 v12, v98, v12
	v_cvt_pk_bf16_f32 v12, v12, s0
	ds_write_b16 v106, v13 offset:6800
	ds_write_b16_d16_hi v106, v13 offset:41616
	ds_write_b16 v132, v12
	v_add_f32_e32 v13, v14, v26
	v_sub_f32_e32 v14, v13, v15
	v_med3_f32 v14, v14, s63, v152
	v_mul_f32_e32 v14, 0x3fb8aa3b, v14
	v_exp_f32_e32 v26, v14
	s_waitcnt vmcnt(11)
	v_lshlrev_b32_e32 v28, 16, v166
	v_lshl_or_b32 v12, v167, 16, v165
	v_rcp_f32_e32 v29, v26
	s_nop 0
	v_pk_mul_f32 v[26:27], v[26:27], v[28:29]
	s_nop 0
	v_cvt_pk_bf16_f32 v14, v26, v27
	v_mul_f32_e32 v26, v98, v26
	v_cvt_pk_bf16_f32 v26, v26, s0
	ds_write_b16 v106, v14 offset:7072
	ds_write_b16_d16_hi v106, v14 offset:41888
	ds_write_b16 v133, v26
	v_add_f32_e32 v14, v13, v24
	v_sub_f32_e32 v13, v14, v15
	v_med3_f32 v13, v13, s63, v152
	v_mul_f32_e32 v13, 0x3fb8aa3b, v13
	v_exp_f32_e32 v24, v13
	v_add_f32_e32 v14, v14, v22
	v_sub_f32_e32 v22, v14, v15
	v_med3_f32 v22, v22, s63, v152
	v_rcp_f32_e32 v27, v24
	v_mul_f32_e32 v22, 0x3fb8aa3b, v22
	v_exp_f32_e32 v22, v22
	s_waitcnt vmcnt(9)
	v_lshlrev_b32_e32 v26, 16, v164
	v_pk_mul_f32 v[24:25], v[24:25], v[26:27]
	s_nop 0
	v_cvt_pk_bf16_f32 v13, v24, v25
	v_rcp_f32_e32 v25, v22
	v_mul_f32_e32 v24, v98, v24
	v_cvt_pk_bf16_f32 v24, v24, s0
	ds_write_b16 v106, v13 offset:7344
	ds_write_b16_d16_hi v106, v13 offset:42160
	ds_write_b16 v134, v24
	s_waitcnt vmcnt(7)
; #define LAS __attribute__((address_space(3)))
; __device__ __forceinline__ unsigned f2bf(float f) { unsigned u = __builtin_bit_cast(unsigned, f); return (u + 0x7fffu + ((u >> 16) & 1u)) >> 16; }
; __device__ __forceinline__ int crow(int r, int hi) { return (r & 3) + 8 * (r >> 2) + 4 * hi; }
; __global__ void __launch_bounds__(NT, 2) hymba_fwd(Args args) {
;     ...
;             LAS u32x4* vt = (LAS u32x4*)(lds + 3 * XB + d * (XP * 2) + seg * 64);
; #pragma unroll
;             for (int q = 0; q < 4; ++q) vt[q] = (u32x4){vp[4 * q], vp[4 * q + 1], vp[4 * q + 2], vp[4 * q + 3]};
;             __syncthreads();
;             f32x16 acc[2];
; #pragma unroll
;             for (int r = 0; r < 16; ++r) { acc[0][r] = 0.f; acc[1][r] = 0.f; }
;             mm128(lds + 0 * XB, lds + 1 * XB, acc, wave, lane);
;             __syncthreads();
;             { const int l32 = lane & 31, hh = lane >> 5;
; #pragma unroll
;               for (int nt = 0; nt < 2; ++nt)
; #pragma unroll
;                 for (int r = 0; r < 16; ++r) { const int t = (wave & 3) * 32 + crow(r, hh), s = (wave >> 2) * 64 + 32 * nt + l32; X0[t * XP + s] = (bf16)(s <= t ? f2bf(acc[nt][r]) : 0u); } }
;             {
; #pragma unroll
;               for (int q = 0; q < 4; ++q) { const int e = (q * NT + tid) * 8, rr = e >> 7, cc = e & 127; *(LAS u32x4*)(X1 + rr * XP + cc) = *(const u32x4*)(DST + (size_t)((c - 1) * 4 + h) * 16384 + e); } }
	v_lshlrev_b32_e32 v24, 16, v162
	v_pk_mul_f32 v[22:23], v[22:23], v[24:25]
	v_add_f32_e32 v24, v14, v20
	v_sub_f32_e32 v14, v24, v15
	v_med3_f32 v14, v14, s63, v152
	v_mul_f32_e32 v14, 0x3fb8aa3b, v14
	v_exp_f32_e32 v20, v14
	v_cvt_pk_bf16_f32 v23, v22, v23
	v_mul_f32_e32 v22, v98, v22
	v_cvt_pk_bf16_f32 v22, v22, s0
	ds_write_b16 v106, v23 offset:7616
	ds_write_b16_d16_hi v106, v23 offset:42432
	ds_write_b16 v135, v22
	v_rcp_f32_e32 v23, v20
	s_waitcnt vmcnt(5)
	v_lshlrev_b32_e32 v22, 16, v160
	v_lshl_or_b32 v13, v163, 16, v161
	v_pk_mul_f32 v[20:21], v[20:21], v[22:23]
	v_add_f32_e32 v22, v24, v18
	v_sub_f32_e32 v18, v22, v15
	v_med3_f32 v18, v18, s63, v152
	v_mul_f32_e32 v18, 0x3fb8aa3b, v18
	v_exp_f32_e32 v18, v18
	v_add_f32_e32 v16, v22, v16
	v_sub_f32_e32 v15, v16, v15
	v_cvt_pk_bf16_f32 v14, v20, v21
	v_rcp_f32_e32 v21, v18
	v_med3_f32 v15, v15, s63, v152
	v_mul_f32_e32 v20, v98, v20
	v_mul_f32_e32 v15, 0x3fb8aa3b, v15
	v_cvt_pk_bf16_f32 v20, v20, s0
	v_exp_f32_e32 v16, v15
	ds_write_b16 v106, v14 offset:7888
	ds_write_b16_d16_hi v106, v14 offset:42704
	ds_write_b16 v136, v20
	s_waitcnt vmcnt(3)
	v_lshlrev_b32_e32 v20, 16, v158
	v_pk_mul_f32 v[18:19], v[18:19], v[20:21]
	v_lshl_or_b32 v14, v159, 16, v157
	v_cvt_pk_bf16_f32 v19, v18, v19
	v_mul_f32_e32 v18, v98, v18
	v_cvt_pk_bf16_f32 v18, v18, s0
	ds_write_b16 v106, v19 offset:8160
	ds_write_b16_d16_hi v106, v19 offset:42976
	ds_write_b16 v137, v18
	v_rcp_f32_e32 v19, v16
	s_waitcnt vmcnt(1)
	v_lshlrev_b32_e32 v18, 16, v99
	v_pk_mul_f32 v[16:17], v[16:17], v[18:19]
	s_nop 0
	v_cvt_pk_bf16_f32 v15, v16, v17
	v_mul_f32_e32 v16, v98, v16
	v_cvt_pk_bf16_f32 v16, v16, s0
	ds_write_b16 v106, v15 offset:8432
	ds_write_b16_d16_hi v106, v15 offset:43248
	ds_write_b16 v138, v16
	s_waitcnt vmcnt(0)
	v_lshl_or_b32 v15, v97, 16, v96
	ds_write_b128 v140, v[0:3]
	ds_write_b128 v140, v[4:7] offset:16
	ds_write_b128 v140, v[8:11] offset:32
	ds_write_b128 v140, v[12:15] offset:48
	s_waitcnt lgkmcnt(0)
	s_barrier
	ds_read_b128 v[0:3], v154 offset:43520
	ds_read_b128 v[4:7], v153
	ds_read_b128 v[50:53], v153 offset:32
	ds_read_b128 v[8:11], v154 offset:34816
	ds_read_b128 v[66:69], v154 offset:34848
	s_waitcnt lgkmcnt(1)
	v_mfma_f32_32x32x16_bf16 v[16:31], v[4:7], v[8:11], 0
	ds_read_b128 v[70:73], v154 offset:43552
	v_mfma_f32_32x32x16_bf16 v[0:15], v[4:7], v[0:3], 0
	s_waitcnt lgkmcnt(1)
	v_mfma_f32_32x32x16_bf16 v[16:31], v[50:53], v[66:69], v[16:31]
	s_waitcnt lgkmcnt(0)
	v_mfma_f32_32x32x16_bf16 v[0:15], v[50:53], v[70:73], v[0:15]
	ds_read_b128 v[50:53], v153 offset:64
	ds_read_b128 v[66:69], v154 offset:34880
	ds_read_b128 v[70:73], v154 offset:43584
	s_waitcnt lgkmcnt(1)
	v_mfma_f32_32x32x16_bf16 v[16:31], v[50:53], v[66:69], v[16:31]
	s_waitcnt lgkmcnt(0)
	v_mfma_f32_32x32x16_bf16 v[0:15], v[50:53], v[70:73], v[0:15]
	ds_read_b128 v[50:53], v153 offset:96
	ds_read_b128 v[66:69], v154 offset:34912
	ds_read_b128 v[70:73], v154 offset:43616
	s_waitcnt lgkmcnt(1)
	v_mfma_f32_32x32x16_bf16 v[16:31], v[50:53], v[66:69], v[16:31]
	s_waitcnt lgkmcnt(0)
	v_mfma_f32_32x32x16_bf16 v[0:15], v[50:53], v[70:73], v[0:15]
	ds_read_b128 v[50:53], v153 offset:128
	ds_read_b128 v[66:69], v154 offset:34944
	ds_read_b128 v[70:73], v154 offset:43648
	s_waitcnt lgkmcnt(1)
	v_mfma_f32_32x32x16_bf16 v[16:31], v[50:53], v[66:69], v[16:31]
	s_waitcnt lgkmcnt(0)
	v_mfma_f32_32x32x16_bf16 v[0:15], v[50:53], v[70:73], v[0:15]
	ds_read_b128 v[50:53], v153 offset:160
	ds_read_b128 v[66:69], v154 offset:34976
	ds_read_b128 v[70:73], v154 offset:43680
	s_waitcnt lgkmcnt(1)
	v_mfma_f32_32x32x16_bf16 v[16:31], v[50:53], v[66:69], v[16:31]
	s_waitcnt lgkmcnt(0)
	v_mfma_f32_32x32x16_bf16 v[0:15], v[50:53], v[70:73], v[0:15]
	ds_read_b128 v[50:53], v153 offset:192
	ds_read_b128 v[66:69], v154 offset:35008
	ds_read_b128 v[70:73], v154 offset:43712
	s_waitcnt lgkmcnt(1)
	v_mfma_f32_32x32x16_bf16 v[16:31], v[50:53], v[66:69], v[16:31]
	s_waitcnt lgkmcnt(0)
	v_mfma_f32_32x32x16_bf16 v[0:15], v[50:53], v[70:73], v[0:15]
	ds_read_b128 v[50:53], v153 offset:224
	ds_read_b128 v[66:69], v154 offset:35040
	ds_read_b128 v[70:73], v154 offset:43744
	s_waitcnt lgkmcnt(0)
	s_barrier
	s_mov_b32 s98, 0xffffa000
	s_mov_b32 s99, -1
	v_lshl_add_u64 v[204:205], v[64:65], 0, s[98:99]
	global_load_dwordx4 v[160:163], v[204:205], off
	s_mov_b32 s98, 0xffffc000
	v_lshl_add_u64 v[204:205], v[64:65], 0, s[98:99]
	global_load_dwordx4 v[164:167], v[204:205], off
	s_mov_b32 s98, 0xffffe000
	v_lshl_add_u64 v[204:205], v[64:65], 0, s[98:99]
	global_load_dwordx4 v[168:171], v[204:205], off
	global_load_dwordx4 v[172:175], v[64:65], off
	v_mfma_f32_32x32x16_bf16 v[16:31], v[50:53], v[66:69], v[16:31]
	v_mfma_f32_32x32x16_bf16 v[0:15], v[50:53], v[70:73], v[0:15]
	s_and_saveexec_b64 s[0:1], s[48:49]
	s_nop 9
	v_bfe_u32 v50, v16, 16, 1
	v_add3_u32 v16, v16, v50, s64
	v_lshrrev_b32_e32 v156, 16, v16
	s_or_b64 exec, exec, s[0:1]
	v_mov_b32_e32 v16, 0
	v_mov_b32_e32 v50, 0
	ds_write_b16 v155, v156
	s_and_saveexec_b64 s[0:1], s[40:41]
	v_readlane_b32 s2, v237, 27
	v_readlane_b32 s3, v237, 28
	v_bfe_u32 v50, v17, 16, 1
	v_add3_u32 v17, v17, v50, s64
	v_lshrrev_b32_e32 v50, 16, v17
	s_or_b64 exec, exec, s[0:1]
	ds_write_b16 v155, v50 offset:272
	s_and_saveexec_b64 s[0:1], s[42:43]
	v_bfe_u32 v16, v18, 16, 1
	v_add3_u32 v16, v18, v16, s64
	v_lshrrev_b32_e32 v16, 16, v16
	s_or_b64 exec, exec, s[0:1]
	ds_write_b16 v155, v16 offset:544
	v_mov_b32_e32 v16, 0
	v_mov_b32_e32 v17, 0
	s_and_saveexec_b64 s[0:1], s[54:55]
	v_bfe_u32 v17, v19, 16, 1
	v_add3_u32 v17, v19, v17, s64
	v_lshrrev_b32_e32 v17, 16, v17
	s_or_b64 exec, exec, s[0:1]
	ds_write_b16 v155, v17 offset:816
; __device__ __forceinline__ unsigned f2bf(float f) { unsigned u = __builtin_bit_cast(unsigned, f); return (u + 0x7fffu + ((u >> 16) & 1u)) >> 16; }
; __device__ __forceinline__ int crow(int r, int hi) { return (r & 3) + 8 * (r >> 2) + 4 * hi; }
; __global__ void __launch_bounds__(NT, 2) hymba_fwd(Args args) {
;     ...
;                 for (int r = 0; r < 16; ++r) { const int t = (wave & 3) * 32 + crow(r, hh), s = (wave >> 2) * 64 + 32 * nt + l32; X0[t * XP + s] = (bf16)(s <= t ? f2bf(acc[nt][r]) : 0u); } }
	s_and_saveexec_b64 s[0:1], s[56:57]
	v_bfe_u32 v16, v20, 16, 1
	v_add3_u32 v16, v20, v16, s64
	v_lshrrev_b32_e32 v16, 16, v16
	s_or_b64 exec, exec, s[0:1]
	ds_write_b16 v155, v16 offset:2176
	v_mov_b32_e32 v16, 0
	v_mov_b32_e32 v17, 0
	s_and_saveexec_b64 s[0:1], s[46:47]
	v_bfe_u32 v17, v21, 16, 1
	v_add3_u32 v17, v21, v17, s64
	v_lshrrev_b32_e32 v17, 16, v17
	s_or_b64 exec, exec, s[0:1]
	ds_write_b16 v155, v17 offset:2448
	s_mov_b64 s[0:1], exec
	v_readlane_b32 s4, v237, 48
	v_readlane_b32 s5, v237, 49
	s_and_b64 s[4:5], s[0:1], s[4:5]
	s_mov_b64 exec, s[4:5]
	v_bfe_u32 v16, v22, 16, 1
	v_add3_u32 v16, v22, v16, s64
	v_lshrrev_b32_e32 v16, 16, v16
	s_or_b64 exec, exec, s[0:1]
	ds_write_b16 v155, v16 offset:2720
	v_mov_b32_e32 v16, 0
	v_mov_b32_e32 v17, 0
	s_mov_b64 s[0:1], exec
	v_readlane_b32 s4, v237, 42
	v_readlane_b32 s5, v237, 43
	s_and_b64 s[4:5], s[0:1], s[4:5]
	s_mov_b64 exec, s[4:5]
	v_bfe_u32 v17, v23, 16, 1
	v_add3_u32 v17, v23, v17, s64
	v_lshrrev_b32_e32 v17, 16, v17
	s_or_b64 exec, exec, s[0:1]
	ds_write_b16 v155, v17 offset:2992
	s_mov_b64 s[0:1], exec
	v_readlane_b32 s4, v237, 57
	v_readlane_b32 s5, v237, 58
	s_and_b64 s[4:5], s[0:1], s[4:5]
	s_mov_b64 exec, s[4:5]
	v_bfe_u32 v16, v24, 16, 1
	v_add3_u32 v16, v24, v16, s64
	v_lshrrev_b32_e32 v16, 16, v16
	s_or_b64 exec, exec, s[0:1]
	ds_write_b16 v155, v16 offset:4352
	v_mov_b32_e32 v16, 0
	v_mov_b32_e32 v17, 0
	s_mov_b64 s[0:1], exec
	v_readlane_b32 s4, v237, 59
	v_readlane_b32 s5, v237, 60
	s_and_b64 s[4:5], s[0:1], s[4:5]
	s_mov_b64 exec, s[4:5]
	v_bfe_u32 v17, v25, 16, 1
	v_add3_u32 v17, v25, v17, s64
	v_lshrrev_b32_e32 v17, 16, v17
	s_or_b64 exec, exec, s[0:1]
	ds_write_b16 v155, v17 offset:4624
	s_mov_b64 s[0:1], exec
	v_readlane_b32 s4, v237, 61
	v_readlane_b32 s5, v237, 62
	s_and_b64 s[4:5], s[0:1], s[4:5]
	s_mov_b64 exec, s[4:5]
	v_bfe_u32 v16, v26, 16, 1
	v_add3_u32 v16, v26, v16, s64
	v_lshrrev_b32_e32 v16, 16, v16
	s_or_b64 exec, exec, s[0:1]
	ds_write_b16 v155, v16 offset:4896
	v_mov_b32_e32 v16, 0
	v_mov_b32_e32 v17, 0
	s_mov_b64 s[0:1], exec
	v_readlane_b32 s4, v237, 63
	v_readlane_b32 s5, v236, 0
	s_and_b64 s[4:5], s[0:1], s[4:5]
	s_mov_b64 exec, s[4:5]
	v_bfe_u32 v17, v27, 16, 1
	v_add3_u32 v17, v27, v17, s64
	v_lshrrev_b32_e32 v17, 16, v17
	s_or_b64 exec, exec, s[0:1]
	ds_write_b16 v155, v17 offset:5168
	s_mov_b64 s[0:1], exec
	v_readlane_b32 s4, v236, 1
	v_readlane_b32 s5, v236, 2
	s_and_b64 s[4:5], s[0:1], s[4:5]
	s_mov_b64 exec, s[4:5]
	v_bfe_u32 v16, v28, 16, 1
	v_add3_u32 v16, v28, v16, s64
	v_lshrrev_b32_e32 v16, 16, v16
	s_or_b64 exec, exec, s[0:1]
	ds_write_b16 v155, v16 offset:6528
	v_mov_b32_e32 v16, 0
	v_mov_b32_e32 v17, 0
	s_mov_b64 s[0:1], exec
	v_readlane_b32 s4, v236, 3
	v_readlane_b32 s5, v236, 4
	s_and_b64 s[4:5], s[0:1], s[4:5]
	s_mov_b64 exec, s[4:5]
	v_bfe_u32 v17, v29, 16, 1
	v_add3_u32 v17, v29, v17, s64
	v_lshrrev_b32_e32 v17, 16, v17
	s_or_b64 exec, exec, s[0:1]
	ds_write_b16 v155, v17 offset:6800
	s_mov_b64 s[0:1], exec
	v_readlane_b32 s4, v236, 5
	v_readlane_b32 s5, v236, 6
	s_and_b64 s[4:5], s[0:1], s[4:5]
	s_mov_b64 exec, s[4:5]
	v_bfe_u32 v16, v30, 16, 1
	v_add3_u32 v16, v30, v16, s64
	v_lshrrev_b32_e32 v16, 16, v16
	s_or_b64 exec, exec, s[0:1]
	ds_write_b16 v155, v16 offset:7072
	v_mov_b32_e32 v16, 0
	v_mov_b32_e32 v17, 0
	s_mov_b64 s[0:1], exec
	v_readlane_b32 s4, v236, 7
	v_readlane_b32 s5, v236, 8
	s_and_b64 s[4:5], s[0:1], s[4:5]
	s_mov_b64 exec, s[4:5]
	v_bfe_u32 v17, v31, 16, 1
	v_add3_u32 v17, v31, v17, s64
	v_lshrrev_b32_e32 v17, 16, v17
	s_or_b64 exec, exec, s[0:1]
	ds_write_b16 v155, v17 offset:7344
	s_mov_b64 s[0:1], exec
	v_readlane_b32 s4, v236, 9
	v_readlane_b32 s5, v236, 10
	s_and_b64 s[4:5], s[0:1], s[4:5]
	s_mov_b64 exec, s[4:5]
	v_bfe_u32 v16, v0, 16, 1
	v_add3_u32 v0, v0, v16, s64
	v_lshrrev_b32_e32 v16, 16, v0
	s_or_b64 exec, exec, s[0:1]
	ds_write_b16 v155, v16 offset:64
	v_mov_b32_e32 v0, 0
	v_mov_b32_e32 v16, 0
	s_mov_b64 s[0:1], exec
	v_readlane_b32 s4, v236, 11
	v_readlane_b32 s5, v236, 12
	s_and_b64 s[4:5], s[0:1], s[4:5]
	s_mov_b64 exec, s[4:5]
	v_bfe_u32 v16, v1, 16, 1
	v_add3_u32 v1, v1, v16, s64
	v_lshrrev_b32_e32 v16, 16, v1
	s_or_b64 exec, exec, s[0:1]
	ds_write_b16 v155, v16 offset:336
	s_mov_b64 s[0:1], exec
; __device__ __forceinline__ unsigned f2bf(float f) { unsigned u = __builtin_bit_cast(unsigned, f); return (u + 0x7fffu + ((u >> 16) & 1u)) >> 16; }
; __device__ __forceinline__ int crow(int r, int hi) { return (r & 3) + 8 * (r >> 2) + 4 * hi; }
; __global__ void __launch_bounds__(NT, 2) hymba_fwd(Args args) {
;     ...
;                 for (int r = 0; r < 16; ++r) { const int t = (wave & 3) * 32 + crow(r, hh), s = (wave >> 2) * 64 + 32 * nt + l32; X0[t * XP + s] = (bf16)(s <= t ? f2bf(acc[nt][r]) : 0u); } }
	v_readlane_b32 s4, v236, 13
	v_readlane_b32 s5, v236, 14
	s_and_b64 s[4:5], s[0:1], s[4:5]
	s_mov_b64 exec, s[4:5]
	v_bfe_u32 v0, v2, 16, 1
	v_add3_u32 v0, v2, v0, s64
	v_lshrrev_b32_e32 v0, 16, v0
	s_or_b64 exec, exec, s[0:1]
	ds_write_b16 v155, v0 offset:608
	v_mov_b32_e32 v0, 0
	v_mov_b32_e32 v1, 0
	s_mov_b64 s[0:1], exec
	v_readlane_b32 s4, v236, 15
	v_readlane_b32 s5, v236, 16
	s_and_b64 s[4:5], s[0:1], s[4:5]
	s_mov_b64 exec, s[4:5]
	v_bfe_u32 v1, v3, 16, 1
	v_add3_u32 v1, v3, v1, s64
	v_lshrrev_b32_e32 v1, 16, v1
	s_or_b64 exec, exec, s[0:1]
	ds_write_b16 v155, v1 offset:880
	s_mov_b64 s[0:1], exec
	v_readlane_b32 s4, v236, 17
	v_readlane_b32 s5, v236, 18
	s_and_b64 s[4:5], s[0:1], s[4:5]
	s_mov_b64 exec, s[4:5]
	v_bfe_u32 v0, v4, 16, 1
	v_add3_u32 v0, v4, v0, s64
	v_lshrrev_b32_e32 v0, 16, v0
	s_or_b64 exec, exec, s[0:1]
	ds_write_b16 v155, v0 offset:2240
	v_mov_b32_e32 v0, 0
	v_mov_b32_e32 v1, 0
	s_mov_b64 s[0:1], exec
	v_readlane_b32 s4, v236, 19
	v_readlane_b32 s5, v236, 20
	s_and_b64 s[4:5], s[0:1], s[4:5]
	s_mov_b64 exec, s[4:5]
	v_bfe_u32 v1, v5, 16, 1
	v_add3_u32 v1, v5, v1, s64
	v_lshrrev_b32_e32 v1, 16, v1
	s_or_b64 exec, exec, s[0:1]
	ds_write_b16 v155, v1 offset:2512
	s_mov_b64 s[0:1], exec
	v_readlane_b32 s4, v236, 21
	v_readlane_b32 s5, v236, 22
	s_and_b64 s[4:5], s[0:1], s[4:5]
	s_mov_b64 exec, s[4:5]
	v_bfe_u32 v0, v6, 16, 1
	v_add3_u32 v0, v6, v0, s64
	v_lshrrev_b32_e32 v0, 16, v0
	s_or_b64 exec, exec, s[0:1]
	ds_write_b16 v155, v0 offset:2784
	v_mov_b32_e32 v0, 0
	v_mov_b32_e32 v1, 0
	s_mov_b64 s[0:1], exec
	v_readlane_b32 s4, v236, 23
	v_readlane_b32 s5, v236, 24
	s_and_b64 s[4:5], s[0:1], s[4:5]
	s_mov_b64 exec, s[4:5]
	v_bfe_u32 v1, v7, 16, 1
	v_add3_u32 v1, v7, v1, s64
	v_lshrrev_b32_e32 v1, 16, v1
	s_or_b64 exec, exec, s[0:1]
	ds_write_b16 v155, v1 offset:3056
	s_mov_b64 s[0:1], exec
	v_readlane_b32 s4, v236, 25
	v_readlane_b32 s5, v236, 26
	s_and_b64 s[4:5], s[0:1], s[4:5]
	s_mov_b64 exec, s[4:5]
	v_bfe_u32 v0, v8, 16, 1
	v_add3_u32 v0, v8, v0, s64
	v_lshrrev_b32_e32 v0, 16, v0
	s_or_b64 exec, exec, s[0:1]
	ds_write_b16 v155, v0 offset:4416
	v_mov_b32_e32 v0, 0
	v_mov_b32_e32 v1, 0
	s_mov_b64 s[0:1], exec
	v_readlane_b32 s4, v236, 27
	v_readlane_b32 s5, v236, 28
	s_and_b64 s[4:5], s[0:1], s[4:5]
	s_mov_b64 exec, s[4:5]
	v_bfe_u32 v1, v9, 16, 1
	v_add3_u32 v1, v9, v1, s64
	v_lshrrev_b32_e32 v1, 16, v1
	s_or_b64 exec, exec, s[0:1]
	ds_write_b16 v155, v1 offset:4688
	s_mov_b64 s[0:1], exec
	v_readlane_b32 s4, v236, 29
	v_readlane_b32 s5, v236, 30
	s_and_b64 s[4:5], s[0:1], s[4:5]
	s_mov_b64 exec, s[4:5]
	v_bfe_u32 v0, v10, 16, 1
	v_add3_u32 v0, v10, v0, s64
	v_lshrrev_b32_e32 v0, 16, v0
	s_or_b64 exec, exec, s[0:1]
	ds_write_b16 v155, v0 offset:4960
	v_mov_b32_e32 v0, 0
	v_mov_b32_e32 v1, 0
	s_mov_b64 s[0:1], exec
	v_readlane_b32 s4, v236, 31
	v_readlane_b32 s5, v236, 32
	s_and_b64 s[4:5], s[0:1], s[4:5]
	s_mov_b64 exec, s[4:5]
	v_bfe_u32 v1, v11, 16, 1
	v_add3_u32 v1, v11, v1, s64
	v_lshrrev_b32_e32 v1, 16, v1
	s_or_b64 exec, exec, s[0:1]
	ds_write_b16 v155, v1 offset:5232
	s_mov_b64 s[0:1], exec
	v_readlane_b32 s4, v236, 33
	v_readlane_b32 s5, v236, 34
	s_and_b64 s[4:5], s[0:1], s[4:5]
	s_mov_b64 exec, s[4:5]
	v_bfe_u32 v0, v12, 16, 1
	v_add3_u32 v0, v12, v0, s64
	v_lshrrev_b32_e32 v0, 16, v0
	s_or_b64 exec, exec, s[0:1]
	ds_write_b16 v155, v0 offset:6592
	v_mov_b32_e32 v0, 0
	v_mov_b32_e32 v1, 0
	s_mov_b64 s[0:1], exec
	v_readlane_b32 s4, v236, 35
	v_readlane_b32 s5, v236, 36
	s_and_b64 s[4:5], s[0:1], s[4:5]
	s_mov_b64 exec, s[4:5]
	v_bfe_u32 v1, v13, 16, 1
	v_add3_u32 v1, v13, v1, s64
	v_lshrrev_b32_e32 v1, 16, v1
	s_or_b64 exec, exec, s[0:1]
	ds_write_b16 v155, v1 offset:6864
	s_mov_b64 s[0:1], exec
	v_readlane_b32 s4, v236, 37
	v_readlane_b32 s5, v236, 38
	s_and_b64 s[4:5], s[0:1], s[4:5]
	s_mov_b64 exec, s[4:5]
	v_bfe_u32 v0, v14, 16, 1
	v_add3_u32 v0, v14, v0, s64
	v_lshrrev_b32_e32 v0, 16, v0
	s_or_b64 exec, exec, s[0:1]
	ds_write_b16 v155, v0 offset:7136
	v_mov_b32_e32 v0, 0
	s_mov_b64 s[0:1], exec
	v_readlane_b32 s4, v236, 43
	v_readlane_b32 s5, v236, 44
	s_and_b64 s[4:5], s[0:1], s[4:5]
	s_mov_b64 exec, s[4:5]
	s_cbranch_execz .LBB0_1120
	v_bfe_u32 v0, v15, 16, 1
	v_add3_u32 v0, v15, v0, s64
	v_lshrrev_b32_e32 v0, 16, v0
	s_branch .LBB0_1120
